# hand-off version with the mid-block s_setprio 0/1 pair removed from each 32-MFMA block
# baseline (speedup 1.0000x reference)
; #define PG8_STAGE(bufoff, gbase, voff) do { _Pragma("unroll") for (int _i = 0; _i < 2; ++_i) \
;         __builtin_amdgcn_global_load_lds((const unsigned*)((const char*)(gbase) + (voff)[_i]), (LAS unsigned*)(lds + (bufoff) + ldsw + _i * 8192), 16, 0, 0); } while (0)
; #define PG8_LDA(dst, b, h) do { _Pragma("unroll") for (int m = 0; m < 4; ++m) _Pragma("unroll") for (int k = 0; k < 2; ++k) dst[m][k] = *(const LAS bf16x8*)(lds + PG8_SA(b, h) + aoff + m * 2048 + k * 1024); } while (0)
; #define PG8_LDB(dst, b, h) do { _Pragma("unroll") for (int n = 0; n < 2; ++n) _Pragma("unroll") for (int k = 0; k < 2; ++k) dst[n][k] = *(const LAS bf16x8*)(lds + PG8_SB(b, h) + boff + n * 2048 + k * 1024); } while (0)
; #define PG8_MMA(ai, bj, At, Bt) do { __builtin_amdgcn_s_setprio(1); _Pragma("unroll") for (int m = 0; m < 4; ++m) _Pragma("unroll") for (int n = 0; n < 2; ++n) _Pragma("unroll") for (int k = 0; k < 2; ++k) \
;         acc[ai][bj][m][n] = __builtin_amdgcn_mfma_f32_16x16x32_bf16(Bt[n][k], At[m][k], acc[ai][bj][m][n], 0, 0, 0); __builtin_amdgcn_s_setprio(0); } while (0)
; #define PG8_WAIT_V(n) asm volatile("s_waitcnt vmcnt(" #n ")" ::: "memory")
; #define PG8_WAIT_L(n) asm volatile("s_waitcnt lgkmcnt(" #n ")" ::: "memory")
; #define PG8_BAR __builtin_amdgcn_s_barrier()
; #define PG8_SCHED __builtin_amdgcn_sched_barrier(0)
; template <class Epi, class Sched>
; __device__ __forceinline__ void gemm_phase(LAS unsigned char* lds, const int K, const Sched& S, const Epi& E) {
;     ...
;             const bool last = (t == nt - 2);
;             const char* a1 = cA + (size_t)(t + 1) * kstep;
;             const char* a2 = last ? nA : cA + (size_t)(t + 2) * kstep; const char* b2 = last ? nB : cB + (size_t)(t + 2) * kstep;
;             const char* a3 = a2 + kstep; const char* b3 = b2 + kstep;
;             PG8_LDB(B0, 0, 0); PG8_LDB(B1, 0, 1); PG8_SCHED; PG8_LDA(At, 0, 0); PG8_STAGE(PG8_SA(1, 1), a1 + hstep, voffA);
;             PG8_WAIT_V(8); PG8_WAIT_L(0); PG8_BAR; PG8_MMA(0, 0, At, B0); PG8_MMA(0, 1, At, B1); PG8_BAR; PG8_SCHED;
;             PG8_LDA(At, 0, 1); PG8_STAGE(PG8_SB(0, 0), b2, voffB); PG8_STAGE(PG8_SB(0, 1), b2 + hstep, voffB); PG8_STAGE(PG8_SA(0, 0), a2, voffA);
.LBB0_403:
	s_add_u32 s14, s8, 0xfffc0080
	s_addc_u32 s15, s9, -1
	s_add_i32 s16, 0, 0x10000
	s_cmp_eq_u32 s13, 12
	s_cselect_b32 s55, s2, s15
	s_cselect_b32 s54, s4, s14
	v_add_u32_e32 v128, s16, v149
	s_cselect_b32 s39, s5, s12
	s_cselect_b32 s38, s10, s11
	s_add_i32 s17, 0, 0x14000
	ds_read_b128 v[158:161], v128
	ds_read_b128 v[162:165], v128 offset:1024
	ds_read_b128 v[184:187], v128 offset:2048
	ds_read_b128 v[188:191], v128 offset:3072
	v_add_u32_e32 v128, s17, v149
	ds_read_b128 v[192:195], v128
	ds_read_b128 v[196:199], v128 offset:1024
	ds_read_b128 v[200:203], v128 offset:2048
	ds_read_b128 v[204:207], v128 offset:3072
	v_lshl_add_u64 v[166:167], s[8:9], 0, v[154:155]
	s_add_i32 m0, s59, 0xc000
	ds_read_b128 v[208:211], v147
	ds_read_b128 v[212:215], v147 offset:1024
	ds_read_b128 v[216:219], v147 offset:2048
	ds_read_b128 v[220:223], v147 offset:3072
	ds_read_b128 v[224:227], v147 offset:4096
	ds_read_b128 v[228:231], v147 offset:5120
	ds_read_b128 v[232:235], v147 offset:6144
	ds_read_b128 v[236:239], v147 offset:7168
	global_load_lds_dwordx4 v[166:167], off
	v_lshl_add_u64 v[166:167], s[8:9], 0, v[156:157]
	s_add_i32 m0, s59, 0xe000
	s_nop 0
	global_load_lds_dwordx4 v[166:167], off
	s_waitcnt vmcnt(8)
	s_waitcnt lgkmcnt(0)
	s_setprio 1
	s_barrier
	v_mfma_f32_16x16x32_bf16 v[124:127], v[158:161], v[208:211], v[124:127]
	v_mfma_f32_16x16x32_bf16 v[120:123], v[184:187], v[208:211], v[120:123]
	v_mfma_f32_16x16x32_bf16 v[108:111], v[158:161], v[216:219], v[108:111]
	v_mfma_f32_16x16x32_bf16 v[104:107], v[184:187], v[216:219], v[104:107]
	v_mfma_f32_16x16x32_bf16 v[92:95], v[158:161], v[224:227], v[92:95]
	v_mfma_f32_16x16x32_bf16 v[88:91], v[184:187], v[224:227], v[88:91]
	v_mfma_f32_16x16x32_bf16 v[76:79], v[158:161], v[232:235], v[76:79]
	v_mfma_f32_16x16x32_bf16 v[72:75], v[184:187], v[232:235], v[72:75]
	v_mfma_f32_16x16x32_bf16 v[124:127], v[162:165], v[212:215], v[124:127]
	v_mfma_f32_16x16x32_bf16 v[120:123], v[188:191], v[212:215], v[120:123]
	v_mfma_f32_16x16x32_bf16 v[108:111], v[162:165], v[220:223], v[108:111]
	v_mfma_f32_16x16x32_bf16 v[104:107], v[188:191], v[220:223], v[104:107]
	v_mfma_f32_16x16x32_bf16 v[92:95], v[162:165], v[228:231], v[92:95]
	v_mfma_f32_16x16x32_bf16 v[88:91], v[188:191], v[228:231], v[88:91]
	v_mfma_f32_16x16x32_bf16 v[76:79], v[162:165], v[236:239], v[76:79]
	v_mfma_f32_16x16x32_bf16 v[72:75], v[188:191], v[236:239], v[72:75]
	v_mfma_f32_16x16x32_bf16 v[116:119], v[192:195], v[208:211], v[116:119]
	v_mfma_f32_16x16x32_bf16 v[112:115], v[200:203], v[208:211], v[112:115]
	v_mfma_f32_16x16x32_bf16 v[100:103], v[192:195], v[216:219], v[100:103]
	v_mfma_f32_16x16x32_bf16 v[96:99], v[200:203], v[216:219], v[96:99]
	v_mfma_f32_16x16x32_bf16 v[84:87], v[192:195], v[224:227], v[84:87]
	v_mfma_f32_16x16x32_bf16 v[80:83], v[200:203], v[224:227], v[80:83]
	v_mfma_f32_16x16x32_bf16 v[68:71], v[192:195], v[232:235], v[68:71]
	v_mfma_f32_16x16x32_bf16 v[64:67], v[200:203], v[232:235], v[64:67]
	v_mfma_f32_16x16x32_bf16 v[116:119], v[196:199], v[212:215], v[116:119]
	v_mfma_f32_16x16x32_bf16 v[112:115], v[204:207], v[212:215], v[112:115]
	v_mfma_f32_16x16x32_bf16 v[100:103], v[196:199], v[220:223], v[100:103]
	v_mfma_f32_16x16x32_bf16 v[96:99], v[204:207], v[220:223], v[96:99]
	v_mfma_f32_16x16x32_bf16 v[84:87], v[196:199], v[228:231], v[84:87]
	v_mfma_f32_16x16x32_bf16 v[80:83], v[204:207], v[228:231], v[80:83]
	v_mfma_f32_16x16x32_bf16 v[68:71], v[196:199], v[236:239], v[68:71]
	v_mfma_f32_16x16x32_bf16 v[64:67], v[204:207], v[236:239], v[64:67]
	s_barrier
	s_setprio 0
	s_add_i32 s14, s16, s58
	v_lshl_add_u64 v[166:167], s[38:39], 0, v[140:141]
	s_mov_b32 m0, s14
	ds_read_b128 v[208:211], v147 offset:16384
	ds_read_b128 v[212:215], v147 offset:17408
	ds_read_b128 v[216:219], v147 offset:18432
	ds_read_b128 v[220:223], v147 offset:19456
	ds_read_b128 v[224:227], v147 offset:20480
	ds_read_b128 v[228:231], v147 offset:21504
	ds_read_b128 v[232:235], v147 offset:22528
	ds_read_b128 v[236:239], v147 offset:23552
	global_load_lds_dwordx4 v[166:167], off
	s_add_i32 m0, s14, 0x2000
	s_add_u32 s14, s38, 0x40000
	v_lshl_add_u64 v[180:181], s[38:39], 0, v[144:145]
	s_addc_u32 s15, s39, 0
	s_add_i32 s16, s17, s58
	global_load_lds_dwordx4 v[180:181], off
	v_lshl_add_u64 v[182:183], s[14:15], 0, v[140:141]
	s_mov_b32 m0, s16
	v_lshl_add_u64 v[240:241], s[54:55], 0, v[142:143]
	global_load_lds_dwordx4 v[182:183], off
	v_lshl_add_u64 v[182:183], s[14:15], 0, v[144:145]
	s_add_i32 m0, s16, 0x2000
	s_nop 0
	global_load_lds_dwordx4 v[182:183], off
	v_lshl_add_u64 v[182:183], s[54:55], 0, v[138:139]
	s_mov_b32 m0, s59
	s_nop 0
	global_load_lds_dwordx4 v[182:183], off
	s_mov_b32 m0, s60
	s_nop 0
	global_load_lds_dwordx4 v[240:241], off
	s_waitcnt vmcnt(8)
	s_waitcnt lgkmcnt(0)
	s_setprio 1
	s_barrier
; #define PG8_STAGE(bufoff, gbase, voff) do { _Pragma("unroll") for (int _i = 0; _i < 2; ++_i) \
;         __builtin_amdgcn_global_load_lds((const unsigned*)((const char*)(gbase) + (voff)[_i]), (LAS unsigned*)(lds + (bufoff) + ldsw + _i * 8192), 16, 0, 0); } while (0)
; #define PG8_LDA(dst, b, h) do { _Pragma("unroll") for (int m = 0; m < 4; ++m) _Pragma("unroll") for (int k = 0; k < 2; ++k) dst[m][k] = *(const LAS bf16x8*)(lds + PG8_SA(b, h) + aoff + m * 2048 + k * 1024); } while (0)
; #define PG8_LDB(dst, b, h) do { _Pragma("unroll") for (int n = 0; n < 2; ++n) _Pragma("unroll") for (int k = 0; k < 2; ++k) dst[n][k] = *(const LAS bf16x8*)(lds + PG8_SB(b, h) + boff + n * 2048 + k * 1024); } while (0)
; #define PG8_MMA(ai, bj, At, Bt) do { __builtin_amdgcn_s_setprio(1); _Pragma("unroll") for (int m = 0; m < 4; ++m) _Pragma("unroll") for (int n = 0; n < 2; ++n) _Pragma("unroll") for (int k = 0; k < 2; ++k) \
;         acc[ai][bj][m][n] = __builtin_amdgcn_mfma_f32_16x16x32_bf16(Bt[n][k], At[m][k], acc[ai][bj][m][n], 0, 0, 0); __builtin_amdgcn_s_setprio(0); } while (0)
; #define PG8_WAIT_V(n) asm volatile("s_waitcnt vmcnt(" #n ")" ::: "memory")
; #define PG8_WAIT_L(n) asm volatile("s_waitcnt lgkmcnt(" #n ")" ::: "memory")
; #define PG8_BAR __builtin_amdgcn_s_barrier()
; #define PG8_SCHED __builtin_amdgcn_sched_barrier(0)
; template <class Epi, class Sched>
; __device__ __forceinline__ void gemm_phase(LAS unsigned char* lds, const int K, const Sched& S, const Epi& E) {
;     ...
;             PG8_WAIT_V(8); PG8_WAIT_L(0); PG8_BAR; PG8_MMA(1, 0, At, B0); PG8_MMA(1, 1, At, B1); PG8_BAR; PG8_SCHED;
;             PG8_LDB(B0, 1, 0); PG8_LDB(B1, 1, 1); PG8_SCHED; PG8_LDA(At, 1, 0); PG8_STAGE(PG8_SA(0, 1), a2 + hstep, voffA);
;             PG8_WAIT_V(8); PG8_WAIT_L(0); PG8_BAR; PG8_MMA(0, 0, At, B0); PG8_MMA(0, 1, At, B1); PG8_BAR; PG8_SCHED;
	v_mfma_f32_16x16x32_bf16 v[60:63], v[158:161], v[208:211], v[60:63]
	v_mfma_f32_16x16x32_bf16 v[56:59], v[184:187], v[208:211], v[56:59]
	v_mfma_f32_16x16x32_bf16 v[44:47], v[158:161], v[216:219], v[44:47]
	v_mfma_f32_16x16x32_bf16 v[40:43], v[184:187], v[216:219], v[40:43]
	v_mfma_f32_16x16x32_bf16 v[28:31], v[158:161], v[224:227], v[28:31]
	v_mfma_f32_16x16x32_bf16 v[24:27], v[184:187], v[224:227], v[24:27]
	v_mfma_f32_16x16x32_bf16 v[12:15], v[158:161], v[232:235], v[12:15]
	v_mfma_f32_16x16x32_bf16 v[8:11], v[184:187], v[232:235], v[8:11]
	v_mfma_f32_16x16x32_bf16 v[60:63], v[162:165], v[212:215], v[60:63]
	v_mfma_f32_16x16x32_bf16 v[56:59], v[188:191], v[212:215], v[56:59]
	v_mfma_f32_16x16x32_bf16 v[44:47], v[162:165], v[220:223], v[44:47]
	v_mfma_f32_16x16x32_bf16 v[40:43], v[188:191], v[220:223], v[40:43]
	v_mfma_f32_16x16x32_bf16 v[28:31], v[162:165], v[228:231], v[28:31]
	v_mfma_f32_16x16x32_bf16 v[24:27], v[188:191], v[228:231], v[24:27]
	v_mfma_f32_16x16x32_bf16 v[12:15], v[162:165], v[236:239], v[12:15]
	v_mfma_f32_16x16x32_bf16 v[8:11], v[188:191], v[236:239], v[8:11]
	v_mfma_f32_16x16x32_bf16 v[52:55], v[192:195], v[208:211], v[52:55]
	v_mfma_f32_16x16x32_bf16 v[48:51], v[200:203], v[208:211], v[48:51]
	v_mfma_f32_16x16x32_bf16 v[36:39], v[192:195], v[216:219], v[36:39]
	v_mfma_f32_16x16x32_bf16 v[32:35], v[200:203], v[216:219], v[32:35]
	v_mfma_f32_16x16x32_bf16 v[20:23], v[192:195], v[224:227], v[20:23]
	v_mfma_f32_16x16x32_bf16 v[16:19], v[200:203], v[224:227], v[16:19]
	v_mfma_f32_16x16x32_bf16 v[4:7], v[192:195], v[232:235], v[4:7]
	v_mfma_f32_16x16x32_bf16 v[0:3], v[200:203], v[232:235], v[0:3]
	v_mfma_f32_16x16x32_bf16 v[52:55], v[196:199], v[212:215], v[52:55]
	v_mfma_f32_16x16x32_bf16 v[48:51], v[204:207], v[212:215], v[48:51]
	v_mfma_f32_16x16x32_bf16 v[36:39], v[196:199], v[220:223], v[36:39]
	v_mfma_f32_16x16x32_bf16 v[32:35], v[204:207], v[220:223], v[32:35]
	v_mfma_f32_16x16x32_bf16 v[20:23], v[196:199], v[228:231], v[20:23]
	v_mfma_f32_16x16x32_bf16 v[16:19], v[204:207], v[228:231], v[16:19]
	v_mfma_f32_16x16x32_bf16 v[4:7], v[196:199], v[236:239], v[4:7]
	v_mfma_f32_16x16x32_bf16 v[0:3], v[204:207], v[236:239], v[0:3]
	s_barrier
	s_setprio 0
	s_add_i32 s16, 0, 0x18000
	v_add_u32_e32 v128, s16, v149
	s_add_i32 s17, 0, 0x1c000
	ds_read_b128 v[158:161], v128
	ds_read_b128 v[162:165], v128 offset:1024
	ds_read_b128 v[184:187], v128 offset:2048
	ds_read_b128 v[188:191], v128 offset:3072
	v_add_u32_e32 v128, s17, v149
	ds_read_b128 v[192:195], v128
	ds_read_b128 v[196:199], v128 offset:1024
	ds_read_b128 v[200:203], v128 offset:2048
	ds_read_b128 v[204:207], v128 offset:3072
	s_add_u32 s14, s54, 0x40000
	s_addc_u32 s15, s55, 0
	s_mov_b32 m0, s61
	v_lshl_add_u64 v[242:243], s[14:15], 0, v[138:139]
	ds_read_b128 v[208:211], v147 offset:32768
	ds_read_b128 v[212:215], v147 offset:33792
	ds_read_b128 v[216:219], v147 offset:34816
	ds_read_b128 v[220:223], v147 offset:35840
	ds_read_b128 v[224:227], v147 offset:36864
	ds_read_b128 v[228:231], v147 offset:37888
	ds_read_b128 v[232:235], v147 offset:38912
	ds_read_b128 v[236:239], v147 offset:39936
	global_load_lds_dwordx4 v[242:243], off
	v_lshl_add_u64 v[242:243], s[14:15], 0, v[142:143]
	s_mov_b32 m0, s62
	s_nop 0
	global_load_lds_dwordx4 v[242:243], off
	s_waitcnt vmcnt(8)
	s_waitcnt lgkmcnt(0)
	s_setprio 1
	s_barrier
	v_mfma_f32_16x16x32_bf16 v[124:127], v[158:161], v[208:211], v[124:127]
	v_mfma_f32_16x16x32_bf16 v[120:123], v[184:187], v[208:211], v[120:123]
	v_mfma_f32_16x16x32_bf16 v[108:111], v[158:161], v[216:219], v[108:111]
	v_mfma_f32_16x16x32_bf16 v[104:107], v[184:187], v[216:219], v[104:107]
	v_mfma_f32_16x16x32_bf16 v[92:95], v[158:161], v[224:227], v[92:95]
	v_mfma_f32_16x16x32_bf16 v[88:91], v[184:187], v[224:227], v[88:91]
	v_mfma_f32_16x16x32_bf16 v[76:79], v[158:161], v[232:235], v[76:79]
	v_mfma_f32_16x16x32_bf16 v[72:75], v[184:187], v[232:235], v[72:75]
	v_mfma_f32_16x16x32_bf16 v[124:127], v[162:165], v[212:215], v[124:127]
	v_mfma_f32_16x16x32_bf16 v[120:123], v[188:191], v[212:215], v[120:123]
	v_mfma_f32_16x16x32_bf16 v[108:111], v[162:165], v[220:223], v[108:111]
	v_mfma_f32_16x16x32_bf16 v[104:107], v[188:191], v[220:223], v[104:107]
	v_mfma_f32_16x16x32_bf16 v[92:95], v[162:165], v[228:231], v[92:95]
	v_mfma_f32_16x16x32_bf16 v[88:91], v[188:191], v[228:231], v[88:91]
	v_mfma_f32_16x16x32_bf16 v[76:79], v[162:165], v[236:239], v[76:79]
	v_mfma_f32_16x16x32_bf16 v[72:75], v[188:191], v[236:239], v[72:75]
	v_mfma_f32_16x16x32_bf16 v[116:119], v[192:195], v[208:211], v[116:119]
	v_mfma_f32_16x16x32_bf16 v[112:115], v[200:203], v[208:211], v[112:115]
	v_mfma_f32_16x16x32_bf16 v[100:103], v[192:195], v[216:219], v[100:103]
	v_mfma_f32_16x16x32_bf16 v[96:99], v[200:203], v[216:219], v[96:99]
	v_mfma_f32_16x16x32_bf16 v[84:87], v[192:195], v[224:227], v[84:87]
	v_mfma_f32_16x16x32_bf16 v[80:83], v[200:203], v[224:227], v[80:83]
	v_mfma_f32_16x16x32_bf16 v[68:71], v[192:195], v[232:235], v[68:71]
	v_mfma_f32_16x16x32_bf16 v[64:67], v[200:203], v[232:235], v[64:67]
	v_mfma_f32_16x16x32_bf16 v[116:119], v[196:199], v[212:215], v[116:119]
	v_mfma_f32_16x16x32_bf16 v[112:115], v[204:207], v[212:215], v[112:115]
	v_mfma_f32_16x16x32_bf16 v[100:103], v[196:199], v[220:223], v[100:103]
	v_mfma_f32_16x16x32_bf16 v[96:99], v[204:207], v[220:223], v[96:99]
	v_mfma_f32_16x16x32_bf16 v[84:87], v[196:199], v[228:231], v[84:87]
	v_mfma_f32_16x16x32_bf16 v[80:83], v[204:207], v[228:231], v[80:83]
	v_mfma_f32_16x16x32_bf16 v[68:71], v[196:199], v[236:239], v[68:71]
	v_mfma_f32_16x16x32_bf16 v[64:67], v[204:207], v[236:239], v[64:67]
	s_barrier
; #define PG8_STAGE(bufoff, gbase, voff) do { _Pragma("unroll") for (int _i = 0; _i < 2; ++_i) \
;         __builtin_amdgcn_global_load_lds((const unsigned*)((const char*)(gbase) + (voff)[_i]), (LAS unsigned*)(lds + (bufoff) + ldsw + _i * 8192), 16, 0, 0); } while (0)
; #define PG8_LDA(dst, b, h) do { _Pragma("unroll") for (int m = 0; m < 4; ++m) _Pragma("unroll") for (int k = 0; k < 2; ++k) dst[m][k] = *(const LAS bf16x8*)(lds + PG8_SA(b, h) + aoff + m * 2048 + k * 1024); } while (0)
; #define PG8_MMA(ai, bj, At, Bt) do { __builtin_amdgcn_s_setprio(1); _Pragma("unroll") for (int m = 0; m < 4; ++m) _Pragma("unroll") for (int n = 0; n < 2; ++n) _Pragma("unroll") for (int k = 0; k < 2; ++k) \
;         acc[ai][bj][m][n] = __builtin_amdgcn_mfma_f32_16x16x32_bf16(Bt[n][k], At[m][k], acc[ai][bj][m][n], 0, 0, 0); __builtin_amdgcn_s_setprio(0); } while (0)
; #define PG8_WAIT_V(n) asm volatile("s_waitcnt vmcnt(" #n ")" ::: "memory")
; #define PG8_WAIT_L(n) asm volatile("s_waitcnt lgkmcnt(" #n ")" ::: "memory")
; #define PG8_BAR __builtin_amdgcn_s_barrier()
; #define PG8_SCHED __builtin_amdgcn_sched_barrier(0)
; template <class Epi, class Sched>
; __device__ __forceinline__ void gemm_phase(LAS unsigned char* lds, const int K, const Sched& S, const Epi& E) {
;     ...
;             PG8_LDA(At, 1, 1); PG8_STAGE(PG8_SB(1, 0), b3, voffB); PG8_STAGE(PG8_SB(1, 1), b3 + hstep, voffB); PG8_STAGE(PG8_SA(1, 0), a3, voffA);
;             PG8_WAIT_V(8); PG8_WAIT_L(0); PG8_BAR; PG8_MMA(1, 0, At, B0); PG8_MMA(1, 1, At, B1); PG8_BAR; PG8_SCHED;
;         }
;         if (wr == 0) PG8_BAR;
	s_setprio 0
	s_add_i32 s14, s16, s58
	v_lshl_add_u64 v[166:167], v[166:167], 0, s[36:37]
	s_mov_b32 m0, s14
	ds_read_b128 v[208:211], v147 offset:49152
	ds_read_b128 v[212:215], v147 offset:50176
	ds_read_b128 v[216:219], v147 offset:51200
	ds_read_b128 v[220:223], v147 offset:52224
	ds_read_b128 v[224:227], v147 offset:53248
	ds_read_b128 v[228:231], v147 offset:54272
	ds_read_b128 v[232:235], v147 offset:55296
	ds_read_b128 v[236:239], v147 offset:56320
	global_load_lds_dwordx4 v[166:167], off
	s_add_i32 m0, s14, 0x2000
	s_add_u32 s14, s38, 0x40080
	v_lshl_add_u64 v[166:167], v[180:181], 0, s[36:37]
	s_addc_u32 s15, s39, 0
	s_add_i32 s16, s17, s58
	global_load_lds_dwordx4 v[166:167], off
	v_lshl_add_u64 v[166:167], s[14:15], 0, v[140:141]
	s_mov_b32 m0, s16
	s_nop 0
	global_load_lds_dwordx4 v[166:167], off
	v_lshl_add_u64 v[166:167], s[14:15], 0, v[144:145]
	s_add_i32 m0, s16, 0x2000
	s_nop 0
	global_load_lds_dwordx4 v[166:167], off
	v_lshl_add_u64 v[166:167], v[182:183], 0, s[36:37]
	s_mov_b32 m0, s64
	s_nop 0
	global_load_lds_dwordx4 v[166:167], off
	v_lshl_add_u64 v[166:167], v[240:241], 0, s[36:37]
	s_mov_b32 m0, s65
	s_nop 0
	global_load_lds_dwordx4 v[166:167], off
	s_waitcnt vmcnt(8)
	s_waitcnt lgkmcnt(0)
	s_setprio 1
	s_barrier
	v_mfma_f32_16x16x32_bf16 v[60:63], v[158:161], v[208:211], v[60:63]
	v_mfma_f32_16x16x32_bf16 v[56:59], v[184:187], v[208:211], v[56:59]
	v_mfma_f32_16x16x32_bf16 v[44:47], v[158:161], v[216:219], v[44:47]
	v_mfma_f32_16x16x32_bf16 v[40:43], v[184:187], v[216:219], v[40:43]
	v_mfma_f32_16x16x32_bf16 v[28:31], v[158:161], v[224:227], v[28:31]
	v_mfma_f32_16x16x32_bf16 v[24:27], v[184:187], v[224:227], v[24:27]
	v_mfma_f32_16x16x32_bf16 v[12:15], v[158:161], v[232:235], v[12:15]
	v_mfma_f32_16x16x32_bf16 v[8:11], v[184:187], v[232:235], v[8:11]
	v_mfma_f32_16x16x32_bf16 v[60:63], v[162:165], v[212:215], v[60:63]
	v_mfma_f32_16x16x32_bf16 v[56:59], v[188:191], v[212:215], v[56:59]
	v_mfma_f32_16x16x32_bf16 v[44:47], v[162:165], v[220:223], v[44:47]
	v_mfma_f32_16x16x32_bf16 v[40:43], v[188:191], v[220:223], v[40:43]
	v_mfma_f32_16x16x32_bf16 v[28:31], v[162:165], v[228:231], v[28:31]
	v_mfma_f32_16x16x32_bf16 v[24:27], v[188:191], v[228:231], v[24:27]
	v_mfma_f32_16x16x32_bf16 v[12:15], v[162:165], v[236:239], v[12:15]
	v_mfma_f32_16x16x32_bf16 v[8:11], v[188:191], v[236:239], v[8:11]
	v_mfma_f32_16x16x32_bf16 v[52:55], v[192:195], v[208:211], v[52:55]
	v_mfma_f32_16x16x32_bf16 v[48:51], v[200:203], v[208:211], v[48:51]
	v_mfma_f32_16x16x32_bf16 v[36:39], v[192:195], v[216:219], v[36:39]
	v_mfma_f32_16x16x32_bf16 v[32:35], v[200:203], v[216:219], v[32:35]
	v_mfma_f32_16x16x32_bf16 v[20:23], v[192:195], v[224:227], v[20:23]
	v_mfma_f32_16x16x32_bf16 v[16:19], v[200:203], v[224:227], v[16:19]
	v_mfma_f32_16x16x32_bf16 v[4:7], v[192:195], v[232:235], v[4:7]
	v_mfma_f32_16x16x32_bf16 v[0:3], v[200:203], v[232:235], v[0:3]
	v_mfma_f32_16x16x32_bf16 v[52:55], v[196:199], v[212:215], v[52:55]
	v_mfma_f32_16x16x32_bf16 v[48:51], v[204:207], v[212:215], v[48:51]
	v_mfma_f32_16x16x32_bf16 v[36:39], v[196:199], v[220:223], v[36:39]
	v_mfma_f32_16x16x32_bf16 v[32:35], v[204:207], v[220:223], v[32:35]
	v_mfma_f32_16x16x32_bf16 v[20:23], v[196:199], v[228:231], v[20:23]
	v_mfma_f32_16x16x32_bf16 v[16:19], v[204:207], v[228:231], v[16:19]
	v_mfma_f32_16x16x32_bf16 v[4:7], v[196:199], v[236:239], v[4:7]
	v_mfma_f32_16x16x32_bf16 v[0:3], v[204:207], v[236:239], v[0:3]
	s_barrier
	s_setprio 0
	s_add_i32 s13, s13, 2
	s_add_u32 s8, s8, 0x100
	s_addc_u32 s9, s9, 0
	s_add_u32 s11, s11, 0x100
	s_addc_u32 s12, s12, 0
	s_cmp_gt_u32 s13, 13
	s_cbranch_scc0 .LBB0_403
	s_and_b64 vcc, exec, s[42:43]
	s_cbranch_vccz .LBB0_406
	s_barrier

; #define PG8_STAGE(bufoff, gbase, voff) do { _Pragma("unroll") for (int _i = 0; _i < 2; ++_i) \
;         __builtin_amdgcn_global_load_lds((const unsigned*)((const char*)(gbase) + (voff)[_i]), (LAS unsigned*)(lds + (bufoff) + ldsw + _i * 8192), 16, 0, 0); } while (0)
; #define PG8_LDA(dst, b, h) do { _Pragma("unroll") for (int m = 0; m < 4; ++m) _Pragma("unroll") for (int k = 0; k < 2; ++k) dst[m][k] = *(const LAS bf16x8*)(lds + PG8_SA(b, h) + aoff + m * 2048 + k * 1024); } while (0)
; #define PG8_LDB(dst, b, h) do { _Pragma("unroll") for (int n = 0; n < 2; ++n) _Pragma("unroll") for (int k = 0; k < 2; ++k) dst[n][k] = *(const LAS bf16x8*)(lds + PG8_SB(b, h) + boff + n * 2048 + k * 1024); } while (0)
; #define PG8_MMA(ai, bj, At, Bt) do { __builtin_amdgcn_s_setprio(1); _Pragma("unroll") for (int m = 0; m < 4; ++m) _Pragma("unroll") for (int n = 0; n < 2; ++n) _Pragma("unroll") for (int k = 0; k < 2; ++k) \
;         acc[ai][bj][m][n] = __builtin_amdgcn_mfma_f32_16x16x32_bf16(Bt[n][k], At[m][k], acc[ai][bj][m][n], 0, 0, 0); __builtin_amdgcn_s_setprio(0); } while (0)
; #define PG8_WAIT_V(n) asm volatile("s_waitcnt vmcnt(" #n ")" ::: "memory")
; #define PG8_WAIT_L(n) asm volatile("s_waitcnt lgkmcnt(" #n ")" ::: "memory")
; #define PG8_BAR __builtin_amdgcn_s_barrier()
; #define PG8_SCHED __builtin_amdgcn_sched_barrier(0)
; template <class Epi, class Sched>
; __device__ __forceinline__ void gemm_phase(LAS unsigned char* lds, const int K, const Sched& S, const Epi& E) {
;     ...
;             const bool last = (t == nt - 2);
;             const char* a1 = cA + (size_t)(t + 1) * kstep;
;             const char* a2 = last ? nA : cA + (size_t)(t + 2) * kstep; const char* b2 = last ? nB : cB + (size_t)(t + 2) * kstep;
;             const char* a3 = a2 + kstep; const char* b3 = b2 + kstep;
;             PG8_LDB(B0, 0, 0); PG8_LDB(B1, 0, 1); PG8_SCHED; PG8_LDA(At, 0, 0); PG8_STAGE(PG8_SA(1, 1), a1 + hstep, voffA);
;             PG8_WAIT_V(8); PG8_WAIT_L(0); PG8_BAR; PG8_MMA(0, 0, At, B0); PG8_MMA(0, 1, At, B1); PG8_BAR; PG8_SCHED;
;             PG8_LDA(At, 0, 1); PG8_STAGE(PG8_SB(0, 0), b2, voffB); PG8_STAGE(PG8_SB(0, 1), b2 + hstep, voffB); PG8_STAGE(PG8_SA(0, 0), a2, voffA);
.LBB0_511:
	s_add_i32 s14, s8, 0xfaf9e080
	s_cmp_lg_u32 s13, 60
	s_cselect_b32 s14, s14, 0
	s_add_u32 s40, s28, s14
	s_addc_u32 s41, s29, 0
	s_add_i32 s15, 0, 0x10000
	s_add_u32 s38, s34, s14
	s_addc_u32 s39, s35, 0
	s_add_i32 s16, 0, 0x14000
	v_add_u32_e32 v164, s15, v145
	v_add_u32_e32 v180, s16, v145
	ds_read_b128 v[152:155], v164
	ds_read_b128 v[156:159], v164 offset:1024
	ds_read_b128 v[160:163], v164 offset:2048
	ds_read_b128 v[164:167], v164 offset:3072
	ds_read_b128 v[184:187], v180
	ds_read_b128 v[188:191], v180 offset:1024
	ds_read_b128 v[192:195], v180 offset:2048
	ds_read_b128 v[196:199], v180 offset:3072
	v_lshl_add_u64 v[180:181], v[146:147], 0, s[8:9]
	s_add_i32 m0, s2, 0xc000
	ds_read_b128 v[200:203], v151
	ds_read_b128 v[204:207], v151 offset:1024
	ds_read_b128 v[208:211], v151 offset:2048
	ds_read_b128 v[212:215], v151 offset:3072
	ds_read_b128 v[216:219], v151 offset:4096
	ds_read_b128 v[220:223], v151 offset:5120
	ds_read_b128 v[224:227], v151 offset:6144
	ds_read_b128 v[228:231], v151 offset:7168
	global_load_lds_dwordx4 v[180:181], off
	v_lshl_add_u64 v[180:181], v[148:149], 0, s[8:9]
	s_add_i32 m0, s2, 0xe000
	s_nop 0
	global_load_lds_dwordx4 v[180:181], off
	s_waitcnt vmcnt(8)
	s_waitcnt lgkmcnt(0)
	s_setprio 1
	s_barrier
	v_mfma_f32_16x16x32_bf16 v[124:127], v[152:155], v[200:203], v[124:127]
	v_mfma_f32_16x16x32_bf16 v[120:123], v[160:163], v[200:203], v[120:123]
	v_mfma_f32_16x16x32_bf16 v[108:111], v[152:155], v[208:211], v[108:111]
	v_mfma_f32_16x16x32_bf16 v[104:107], v[160:163], v[208:211], v[104:107]
	v_mfma_f32_16x16x32_bf16 v[92:95], v[152:155], v[216:219], v[92:95]
	v_mfma_f32_16x16x32_bf16 v[88:91], v[160:163], v[216:219], v[88:91]
	v_mfma_f32_16x16x32_bf16 v[76:79], v[152:155], v[224:227], v[76:79]
	v_mfma_f32_16x16x32_bf16 v[72:75], v[160:163], v[224:227], v[72:75]
	v_mfma_f32_16x16x32_bf16 v[124:127], v[156:159], v[204:207], v[124:127]
	v_mfma_f32_16x16x32_bf16 v[120:123], v[164:167], v[204:207], v[120:123]
	v_mfma_f32_16x16x32_bf16 v[108:111], v[156:159], v[212:215], v[108:111]
	v_mfma_f32_16x16x32_bf16 v[104:107], v[164:167], v[212:215], v[104:107]
	v_mfma_f32_16x16x32_bf16 v[92:95], v[156:159], v[220:223], v[92:95]
	v_mfma_f32_16x16x32_bf16 v[88:91], v[164:167], v[220:223], v[88:91]
	v_mfma_f32_16x16x32_bf16 v[76:79], v[156:159], v[228:231], v[76:79]
	v_mfma_f32_16x16x32_bf16 v[72:75], v[164:167], v[228:231], v[72:75]
	v_mfma_f32_16x16x32_bf16 v[116:119], v[184:187], v[200:203], v[116:119]
	v_mfma_f32_16x16x32_bf16 v[112:115], v[192:195], v[200:203], v[112:115]
	v_mfma_f32_16x16x32_bf16 v[100:103], v[184:187], v[208:211], v[100:103]
	v_mfma_f32_16x16x32_bf16 v[96:99], v[192:195], v[208:211], v[96:99]
	v_mfma_f32_16x16x32_bf16 v[84:87], v[184:187], v[216:219], v[84:87]
	v_mfma_f32_16x16x32_bf16 v[80:83], v[192:195], v[216:219], v[80:83]
	v_mfma_f32_16x16x32_bf16 v[68:71], v[184:187], v[224:227], v[68:71]
	v_mfma_f32_16x16x32_bf16 v[64:67], v[192:195], v[224:227], v[64:67]
	v_mfma_f32_16x16x32_bf16 v[116:119], v[188:191], v[204:207], v[116:119]
	v_mfma_f32_16x16x32_bf16 v[112:115], v[196:199], v[204:207], v[112:115]
	v_mfma_f32_16x16x32_bf16 v[100:103], v[188:191], v[212:215], v[100:103]
	v_mfma_f32_16x16x32_bf16 v[96:99], v[196:199], v[212:215], v[96:99]
	v_mfma_f32_16x16x32_bf16 v[84:87], v[188:191], v[220:223], v[84:87]
	v_mfma_f32_16x16x32_bf16 v[80:83], v[196:199], v[220:223], v[80:83]
	v_mfma_f32_16x16x32_bf16 v[68:71], v[188:191], v[228:231], v[68:71]
	v_mfma_f32_16x16x32_bf16 v[64:67], v[196:199], v[228:231], v[64:67]
	s_barrier
	s_setprio 0
	s_add_i32 s14, s15, s1
	v_lshl_add_u64 v[180:181], s[38:39], 0, v[128:129]
	s_mov_b32 m0, s14
	ds_read_b128 v[200:203], v151 offset:16384
	ds_read_b128 v[204:207], v151 offset:17408
	ds_read_b128 v[208:211], v151 offset:18432
	ds_read_b128 v[212:215], v151 offset:19456
	ds_read_b128 v[216:219], v151 offset:20480
	ds_read_b128 v[220:223], v151 offset:21504
	ds_read_b128 v[224:227], v151 offset:22528
	ds_read_b128 v[228:231], v151 offset:23552
	global_load_lds_dwordx4 v[180:181], off
	s_add_i32 m0, s14, 0x2000
	s_add_u32 s14, s38, 0x100000
	v_lshl_add_u64 v[182:183], s[38:39], 0, v[138:139]
	s_addc_u32 s15, s39, 0
	s_add_i32 s16, s16, s1
	global_load_lds_dwordx4 v[182:183], off
	v_lshl_add_u64 v[232:233], s[14:15], 0, v[128:129]
	s_mov_b32 m0, s16
	v_lshl_add_u64 v[234:235], s[40:41], 0, v[140:141]
	global_load_lds_dwordx4 v[232:233], off
	v_lshl_add_u64 v[232:233], s[14:15], 0, v[138:139]
	s_add_i32 m0, s16, 0x2000
	s_nop 0
	global_load_lds_dwordx4 v[232:233], off
	v_lshl_add_u64 v[232:233], s[40:41], 0, v[142:143]
	s_mov_b32 m0, s2
	s_nop 0
	global_load_lds_dwordx4 v[232:233], off
	s_mov_b32 m0, s3
	s_nop 0
	global_load_lds_dwordx4 v[234:235], off
	s_waitcnt vmcnt(8)
	s_waitcnt lgkmcnt(0)
	s_setprio 1
	s_barrier
; #define PG8_STAGE(bufoff, gbase, voff) do { _Pragma("unroll") for (int _i = 0; _i < 2; ++_i) \
;         __builtin_amdgcn_global_load_lds((const unsigned*)((const char*)(gbase) + (voff)[_i]), (LAS unsigned*)(lds + (bufoff) + ldsw + _i * 8192), 16, 0, 0); } while (0)
; #define PG8_LDA(dst, b, h) do { _Pragma("unroll") for (int m = 0; m < 4; ++m) _Pragma("unroll") for (int k = 0; k < 2; ++k) dst[m][k] = *(const LAS bf16x8*)(lds + PG8_SA(b, h) + aoff + m * 2048 + k * 1024); } while (0)
; #define PG8_LDB(dst, b, h) do { _Pragma("unroll") for (int n = 0; n < 2; ++n) _Pragma("unroll") for (int k = 0; k < 2; ++k) dst[n][k] = *(const LAS bf16x8*)(lds + PG8_SB(b, h) + boff + n * 2048 + k * 1024); } while (0)
; #define PG8_MMA(ai, bj, At, Bt) do { __builtin_amdgcn_s_setprio(1); _Pragma("unroll") for (int m = 0; m < 4; ++m) _Pragma("unroll") for (int n = 0; n < 2; ++n) _Pragma("unroll") for (int k = 0; k < 2; ++k) \
;         acc[ai][bj][m][n] = __builtin_amdgcn_mfma_f32_16x16x32_bf16(Bt[n][k], At[m][k], acc[ai][bj][m][n], 0, 0, 0); __builtin_amdgcn_s_setprio(0); } while (0)
; #define PG8_WAIT_V(n) asm volatile("s_waitcnt vmcnt(" #n ")" ::: "memory")
; #define PG8_WAIT_L(n) asm volatile("s_waitcnt lgkmcnt(" #n ")" ::: "memory")
; #define PG8_BAR __builtin_amdgcn_s_barrier()
; #define PG8_SCHED __builtin_amdgcn_sched_barrier(0)
; template <class Epi, class Sched>
; __device__ __forceinline__ void gemm_phase(LAS unsigned char* lds, const int K, const Sched& S, const Epi& E) {
;     ...
;             PG8_WAIT_V(8); PG8_WAIT_L(0); PG8_BAR; PG8_MMA(1, 0, At, B0); PG8_MMA(1, 1, At, B1); PG8_BAR; PG8_SCHED;
;             PG8_LDB(B0, 1, 0); PG8_LDB(B1, 1, 1); PG8_SCHED; PG8_LDA(At, 1, 0); PG8_STAGE(PG8_SA(0, 1), a2 + hstep, voffA);
;             PG8_WAIT_V(8); PG8_WAIT_L(0); PG8_BAR; PG8_MMA(0, 0, At, B0); PG8_MMA(0, 1, At, B1); PG8_BAR; PG8_SCHED;
	v_mfma_f32_16x16x32_bf16 v[60:63], v[152:155], v[200:203], v[60:63]
	v_mfma_f32_16x16x32_bf16 v[56:59], v[160:163], v[200:203], v[56:59]
	v_mfma_f32_16x16x32_bf16 v[44:47], v[152:155], v[208:211], v[44:47]
	v_mfma_f32_16x16x32_bf16 v[40:43], v[160:163], v[208:211], v[40:43]
	v_mfma_f32_16x16x32_bf16 v[28:31], v[152:155], v[216:219], v[28:31]
	v_mfma_f32_16x16x32_bf16 v[24:27], v[160:163], v[216:219], v[24:27]
	v_mfma_f32_16x16x32_bf16 v[12:15], v[152:155], v[224:227], v[12:15]
	v_mfma_f32_16x16x32_bf16 v[8:11], v[160:163], v[224:227], v[8:11]
	v_mfma_f32_16x16x32_bf16 v[60:63], v[156:159], v[204:207], v[60:63]
	v_mfma_f32_16x16x32_bf16 v[56:59], v[164:167], v[204:207], v[56:59]
	v_mfma_f32_16x16x32_bf16 v[44:47], v[156:159], v[212:215], v[44:47]
	v_mfma_f32_16x16x32_bf16 v[40:43], v[164:167], v[212:215], v[40:43]
	v_mfma_f32_16x16x32_bf16 v[28:31], v[156:159], v[220:223], v[28:31]
	v_mfma_f32_16x16x32_bf16 v[24:27], v[164:167], v[220:223], v[24:27]
	v_mfma_f32_16x16x32_bf16 v[12:15], v[156:159], v[228:231], v[12:15]
	v_mfma_f32_16x16x32_bf16 v[8:11], v[164:167], v[228:231], v[8:11]
	v_mfma_f32_16x16x32_bf16 v[52:55], v[184:187], v[200:203], v[52:55]
	v_mfma_f32_16x16x32_bf16 v[48:51], v[192:195], v[200:203], v[48:51]
	v_mfma_f32_16x16x32_bf16 v[36:39], v[184:187], v[208:211], v[36:39]
	v_mfma_f32_16x16x32_bf16 v[32:35], v[192:195], v[208:211], v[32:35]
	v_mfma_f32_16x16x32_bf16 v[20:23], v[184:187], v[216:219], v[20:23]
	v_mfma_f32_16x16x32_bf16 v[16:19], v[192:195], v[216:219], v[16:19]
	v_mfma_f32_16x16x32_bf16 v[4:7], v[184:187], v[224:227], v[4:7]
	v_mfma_f32_16x16x32_bf16 v[0:3], v[192:195], v[224:227], v[0:3]
	v_mfma_f32_16x16x32_bf16 v[52:55], v[188:191], v[204:207], v[52:55]
	v_mfma_f32_16x16x32_bf16 v[48:51], v[196:199], v[204:207], v[48:51]
	v_mfma_f32_16x16x32_bf16 v[36:39], v[188:191], v[212:215], v[36:39]
	v_mfma_f32_16x16x32_bf16 v[32:35], v[196:199], v[212:215], v[32:35]
	v_mfma_f32_16x16x32_bf16 v[20:23], v[188:191], v[220:223], v[20:23]
	v_mfma_f32_16x16x32_bf16 v[16:19], v[196:199], v[220:223], v[16:19]
	v_mfma_f32_16x16x32_bf16 v[4:7], v[188:191], v[228:231], v[4:7]
	v_mfma_f32_16x16x32_bf16 v[0:3], v[196:199], v[228:231], v[0:3]
	s_barrier
	s_setprio 0
	s_add_i32 s16, 0, 0x18000
	s_add_i32 s17, 0, 0x1c000
	v_add_u32_e32 v164, s16, v145
	v_add_u32_e32 v196, s17, v145
	ds_read_b128 v[152:155], v164
	ds_read_b128 v[156:159], v164 offset:1024
	ds_read_b128 v[160:163], v164 offset:2048
	ds_read_b128 v[164:167], v164 offset:3072
	ds_read_b128 v[184:187], v196
	ds_read_b128 v[188:191], v196 offset:1024
	ds_read_b128 v[192:195], v196 offset:2048
	ds_read_b128 v[196:199], v196 offset:3072
	s_add_u32 s14, s40, 0x100000
	s_addc_u32 s15, s41, 0
	s_mov_b32 m0, s4
	v_lshl_add_u64 v[236:237], s[14:15], 0, v[142:143]
	ds_read_b128 v[200:203], v151 offset:32768
	ds_read_b128 v[204:207], v151 offset:33792
	ds_read_b128 v[208:211], v151 offset:34816
	ds_read_b128 v[212:215], v151 offset:35840
	ds_read_b128 v[216:219], v151 offset:36864
	ds_read_b128 v[220:223], v151 offset:37888
	ds_read_b128 v[224:227], v151 offset:38912
	ds_read_b128 v[228:231], v151 offset:39936
	global_load_lds_dwordx4 v[236:237], off
	v_lshl_add_u64 v[236:237], s[14:15], 0, v[140:141]
	s_mov_b32 m0, s5
	s_nop 0
	global_load_lds_dwordx4 v[236:237], off
	s_waitcnt vmcnt(8)
	s_waitcnt lgkmcnt(0)
	s_setprio 1
	s_barrier
	v_mfma_f32_16x16x32_bf16 v[124:127], v[152:155], v[200:203], v[124:127]
	v_mfma_f32_16x16x32_bf16 v[120:123], v[160:163], v[200:203], v[120:123]
	v_mfma_f32_16x16x32_bf16 v[108:111], v[152:155], v[208:211], v[108:111]
	v_mfma_f32_16x16x32_bf16 v[104:107], v[160:163], v[208:211], v[104:107]
	v_mfma_f32_16x16x32_bf16 v[92:95], v[152:155], v[216:219], v[92:95]
	v_mfma_f32_16x16x32_bf16 v[88:91], v[160:163], v[216:219], v[88:91]
	v_mfma_f32_16x16x32_bf16 v[76:79], v[152:155], v[224:227], v[76:79]
	v_mfma_f32_16x16x32_bf16 v[72:75], v[160:163], v[224:227], v[72:75]
	v_mfma_f32_16x16x32_bf16 v[124:127], v[156:159], v[204:207], v[124:127]
	v_mfma_f32_16x16x32_bf16 v[120:123], v[164:167], v[204:207], v[120:123]
	v_mfma_f32_16x16x32_bf16 v[108:111], v[156:159], v[212:215], v[108:111]
	v_mfma_f32_16x16x32_bf16 v[104:107], v[164:167], v[212:215], v[104:107]
	v_mfma_f32_16x16x32_bf16 v[92:95], v[156:159], v[220:223], v[92:95]
	v_mfma_f32_16x16x32_bf16 v[88:91], v[164:167], v[220:223], v[88:91]
	v_mfma_f32_16x16x32_bf16 v[76:79], v[156:159], v[228:231], v[76:79]
	v_mfma_f32_16x16x32_bf16 v[72:75], v[164:167], v[228:231], v[72:75]
	v_mfma_f32_16x16x32_bf16 v[116:119], v[184:187], v[200:203], v[116:119]
	v_mfma_f32_16x16x32_bf16 v[112:115], v[192:195], v[200:203], v[112:115]
	v_mfma_f32_16x16x32_bf16 v[100:103], v[184:187], v[208:211], v[100:103]
	v_mfma_f32_16x16x32_bf16 v[96:99], v[192:195], v[208:211], v[96:99]
	v_mfma_f32_16x16x32_bf16 v[84:87], v[184:187], v[216:219], v[84:87]
	v_mfma_f32_16x16x32_bf16 v[80:83], v[192:195], v[216:219], v[80:83]
	v_mfma_f32_16x16x32_bf16 v[68:71], v[184:187], v[224:227], v[68:71]
	v_mfma_f32_16x16x32_bf16 v[64:67], v[192:195], v[224:227], v[64:67]
	v_mfma_f32_16x16x32_bf16 v[116:119], v[188:191], v[204:207], v[116:119]
	v_mfma_f32_16x16x32_bf16 v[112:115], v[196:199], v[204:207], v[112:115]
	v_mfma_f32_16x16x32_bf16 v[100:103], v[188:191], v[212:215], v[100:103]
	v_mfma_f32_16x16x32_bf16 v[96:99], v[196:199], v[212:215], v[96:99]
	v_mfma_f32_16x16x32_bf16 v[84:87], v[188:191], v[220:223], v[84:87]
	v_mfma_f32_16x16x32_bf16 v[80:83], v[196:199], v[220:223], v[80:83]
	v_mfma_f32_16x16x32_bf16 v[68:71], v[188:191], v[228:231], v[68:71]
	v_mfma_f32_16x16x32_bf16 v[64:67], v[196:199], v[228:231], v[64:67]
	s_barrier
; #define PG8_STAGE(bufoff, gbase, voff) do { _Pragma("unroll") for (int _i = 0; _i < 2; ++_i) \
;         __builtin_amdgcn_global_load_lds((const unsigned*)((const char*)(gbase) + (voff)[_i]), (LAS unsigned*)(lds + (bufoff) + ldsw + _i * 8192), 16, 0, 0); } while (0)
; #define PG8_LDA(dst, b, h) do { _Pragma("unroll") for (int m = 0; m < 4; ++m) _Pragma("unroll") for (int k = 0; k < 2; ++k) dst[m][k] = *(const LAS bf16x8*)(lds + PG8_SA(b, h) + aoff + m * 2048 + k * 1024); } while (0)
; #define PG8_MMA(ai, bj, At, Bt) do { __builtin_amdgcn_s_setprio(1); _Pragma("unroll") for (int m = 0; m < 4; ++m) _Pragma("unroll") for (int n = 0; n < 2; ++n) _Pragma("unroll") for (int k = 0; k < 2; ++k) \
;         acc[ai][bj][m][n] = __builtin_amdgcn_mfma_f32_16x16x32_bf16(Bt[n][k], At[m][k], acc[ai][bj][m][n], 0, 0, 0); __builtin_amdgcn_s_setprio(0); } while (0)
; #define PG8_WAIT_V(n) asm volatile("s_waitcnt vmcnt(" #n ")" ::: "memory")
; #define PG8_WAIT_L(n) asm volatile("s_waitcnt lgkmcnt(" #n ")" ::: "memory")
; #define PG8_BAR __builtin_amdgcn_s_barrier()
; #define PG8_SCHED __builtin_amdgcn_sched_barrier(0)
; template <class Epi, class Sched>
; __device__ __forceinline__ void gemm_phase(LAS unsigned char* lds, const int K, const Sched& S, const Epi& E) {
;     ...
;             PG8_LDA(At, 1, 1); PG8_STAGE(PG8_SB(1, 0), b3, voffB); PG8_STAGE(PG8_SB(1, 1), b3 + hstep, voffB); PG8_STAGE(PG8_SA(1, 0), a3, voffA);
;             PG8_WAIT_V(8); PG8_WAIT_L(0); PG8_BAR; PG8_MMA(1, 0, At, B0); PG8_MMA(1, 1, At, B1); PG8_BAR; PG8_SCHED;
;         }
;         if (wr == 0) PG8_BAR;
	s_setprio 0
	s_add_i32 s14, s16, s1
	v_lshl_add_u64 v[180:181], v[180:181], 0, s[36:37]
	s_mov_b32 m0, s14
	ds_read_b128 v[200:203], v151 offset:49152
	ds_read_b128 v[204:207], v151 offset:50176
	ds_read_b128 v[208:211], v151 offset:51200
	ds_read_b128 v[212:215], v151 offset:52224
	ds_read_b128 v[216:219], v151 offset:53248
	ds_read_b128 v[220:223], v151 offset:54272
	ds_read_b128 v[224:227], v151 offset:55296
	ds_read_b128 v[228:231], v151 offset:56320
	global_load_lds_dwordx4 v[180:181], off
	s_add_i32 m0, s14, 0x2000
	s_add_u32 s14, s38, 0x100080
	v_lshl_add_u64 v[180:181], v[182:183], 0, s[36:37]
	s_addc_u32 s15, s39, 0
	s_add_i32 s16, s17, s1
	global_load_lds_dwordx4 v[180:181], off
	v_lshl_add_u64 v[180:181], s[14:15], 0, v[128:129]
	s_mov_b32 m0, s16
	s_nop 0
	global_load_lds_dwordx4 v[180:181], off
	v_lshl_add_u64 v[180:181], s[14:15], 0, v[138:139]
	s_add_i32 m0, s16, 0x2000
	s_nop 0
	global_load_lds_dwordx4 v[180:181], off
	v_lshl_add_u64 v[180:181], v[232:233], 0, s[36:37]
	s_mov_b32 m0, s11
	s_nop 0
	global_load_lds_dwordx4 v[180:181], off
	v_lshl_add_u64 v[180:181], v[234:235], 0, s[36:37]
	s_mov_b32 m0, s12
	s_nop 0
	global_load_lds_dwordx4 v[180:181], off
	s_waitcnt vmcnt(8)
	s_waitcnt lgkmcnt(0)
	s_setprio 1
	s_barrier
	v_mfma_f32_16x16x32_bf16 v[60:63], v[152:155], v[200:203], v[60:63]
	v_mfma_f32_16x16x32_bf16 v[56:59], v[160:163], v[200:203], v[56:59]
	v_mfma_f32_16x16x32_bf16 v[44:47], v[152:155], v[208:211], v[44:47]
	v_mfma_f32_16x16x32_bf16 v[40:43], v[160:163], v[208:211], v[40:43]
	v_mfma_f32_16x16x32_bf16 v[28:31], v[152:155], v[216:219], v[28:31]
	v_mfma_f32_16x16x32_bf16 v[24:27], v[160:163], v[216:219], v[24:27]
	v_mfma_f32_16x16x32_bf16 v[12:15], v[152:155], v[224:227], v[12:15]
	v_mfma_f32_16x16x32_bf16 v[8:11], v[160:163], v[224:227], v[8:11]
	v_mfma_f32_16x16x32_bf16 v[60:63], v[156:159], v[204:207], v[60:63]
	v_mfma_f32_16x16x32_bf16 v[56:59], v[164:167], v[204:207], v[56:59]
	v_mfma_f32_16x16x32_bf16 v[44:47], v[156:159], v[212:215], v[44:47]
	v_mfma_f32_16x16x32_bf16 v[40:43], v[164:167], v[212:215], v[40:43]
	v_mfma_f32_16x16x32_bf16 v[28:31], v[156:159], v[220:223], v[28:31]
	v_mfma_f32_16x16x32_bf16 v[24:27], v[164:167], v[220:223], v[24:27]
	v_mfma_f32_16x16x32_bf16 v[12:15], v[156:159], v[228:231], v[12:15]
	v_mfma_f32_16x16x32_bf16 v[8:11], v[164:167], v[228:231], v[8:11]
	v_mfma_f32_16x16x32_bf16 v[52:55], v[184:187], v[200:203], v[52:55]
	v_mfma_f32_16x16x32_bf16 v[48:51], v[192:195], v[200:203], v[48:51]
	v_mfma_f32_16x16x32_bf16 v[36:39], v[184:187], v[208:211], v[36:39]
	v_mfma_f32_16x16x32_bf16 v[32:35], v[192:195], v[208:211], v[32:35]
	v_mfma_f32_16x16x32_bf16 v[20:23], v[184:187], v[216:219], v[20:23]
	v_mfma_f32_16x16x32_bf16 v[16:19], v[192:195], v[216:219], v[16:19]
	v_mfma_f32_16x16x32_bf16 v[4:7], v[184:187], v[224:227], v[4:7]
	v_mfma_f32_16x16x32_bf16 v[0:3], v[192:195], v[224:227], v[0:3]
	v_mfma_f32_16x16x32_bf16 v[52:55], v[188:191], v[204:207], v[52:55]
	v_mfma_f32_16x16x32_bf16 v[48:51], v[196:199], v[204:207], v[48:51]
	v_mfma_f32_16x16x32_bf16 v[36:39], v[188:191], v[212:215], v[36:39]
	v_mfma_f32_16x16x32_bf16 v[32:35], v[196:199], v[212:215], v[32:35]
	v_mfma_f32_16x16x32_bf16 v[20:23], v[188:191], v[220:223], v[20:23]
	v_mfma_f32_16x16x32_bf16 v[16:19], v[196:199], v[220:223], v[16:19]
	v_mfma_f32_16x16x32_bf16 v[4:7], v[188:191], v[228:231], v[4:7]
	v_mfma_f32_16x16x32_bf16 v[0:3], v[196:199], v[228:231], v[0:3]
	s_barrier
	s_setprio 0
	s_add_i32 s13, s13, 2
	s_add_u32 s8, s8, 0x100
	s_addc_u32 s9, s9, 0
	s_cmp_gt_u32 s13, 61
	s_cbranch_scc0 .LBB0_511
	s_cmpk_lt_u32 s0, 0x100
	s_cbranch_scc0 .LBB0_514
	s_barrier

; #define PG8_STAGE(bufoff, gbase, voff) do { _Pragma("unroll") for (int _i = 0; _i < 2; ++_i) \
;         __builtin_amdgcn_global_load_lds((const unsigned*)((const char*)(gbase) + (voff)[_i]), (LAS unsigned*)(lds + (bufoff) + ldsw + _i * 8192), 16, 0, 0); } while (0)
; #define PG8_LDA(dst, b, h) do { _Pragma("unroll") for (int m = 0; m < 4; ++m) _Pragma("unroll") for (int k = 0; k < 2; ++k) dst[m][k] = *(const LAS bf16x8*)(lds + PG8_SA(b, h) + aoff + m * 2048 + k * 1024); } while (0)
; #define PG8_LDB(dst, b, h) do { _Pragma("unroll") for (int n = 0; n < 2; ++n) _Pragma("unroll") for (int k = 0; k < 2; ++k) dst[n][k] = *(const LAS bf16x8*)(lds + PG8_SB(b, h) + boff + n * 2048 + k * 1024); } while (0)
; #define PG8_MMA(ai, bj, At, Bt) do { __builtin_amdgcn_s_setprio(1); _Pragma("unroll") for (int m = 0; m < 4; ++m) _Pragma("unroll") for (int n = 0; n < 2; ++n) _Pragma("unroll") for (int k = 0; k < 2; ++k) \
;         acc[ai][bj][m][n] = __builtin_amdgcn_mfma_f32_16x16x32_bf16(Bt[n][k], At[m][k], acc[ai][bj][m][n], 0, 0, 0); __builtin_amdgcn_s_setprio(0); } while (0)
; #define PG8_WAIT_V(n) asm volatile("s_waitcnt vmcnt(" #n ")" ::: "memory")
; #define PG8_WAIT_L(n) asm volatile("s_waitcnt lgkmcnt(" #n ")" ::: "memory")
; #define PG8_BAR __builtin_amdgcn_s_barrier()
; #define PG8_SCHED __builtin_amdgcn_sched_barrier(0)
; template <class Epi, class Sched>
; __device__ __forceinline__ void gemm_phase(LAS unsigned char* lds, const int K, const Sched& S, const Epi& E) {
;     ...
;         for (int t = 0; t < nt; t += 2) {
;             const bool last = (t == nt - 2);
;             const char* a1 = cA + (size_t)(t + 1) * kstep;
;             const char* a2 = last ? nA : cA + (size_t)(t + 2) * kstep; const char* b2 = last ? nB : cB + (size_t)(t + 2) * kstep;
;             const char* a3 = a2 + kstep; const char* b3 = b2 + kstep;
;             PG8_LDB(B0, 0, 0); PG8_LDB(B1, 0, 1); PG8_SCHED; PG8_LDA(At, 0, 0); PG8_STAGE(PG8_SA(1, 1), a1 + hstep, voffA);
;             PG8_WAIT_V(8); PG8_WAIT_L(0); PG8_BAR; PG8_MMA(0, 0, At, B0); PG8_MMA(0, 1, At, B1); PG8_BAR; PG8_SCHED;
;             PG8_LDA(At, 0, 1); PG8_STAGE(PG8_SB(0, 0), b2, voffB); PG8_STAGE(PG8_SB(0, 1), b2 + hstep, voffB); PG8_STAGE(PG8_SA(0, 0), a2, voffA);
;             PG8_WAIT_V(8); PG8_WAIT_L(0); PG8_BAR; PG8_MMA(1, 0, At, B0); PG8_MMA(1, 1, At, B1); PG8_BAR; PG8_SCHED;
.LBB0_533:
	s_add_u32 s14, s50, s11
	s_addc_u32 s15, s51, 0
	s_add_u32 s16, s14, 0x100
	s_addc_u32 s17, s15, 0
	s_and_b64 s[12:13], s[54:55], exec
	s_cselect_b32 s59, s45, s17
	s_cselect_b32 s58, s44, s16
	s_add_u32 s11, s8, s11
	s_addc_u32 s12, s9, 0
	s_add_u32 s11, s11, 0x100
	s_addc_u32 s16, s12, 0
	s_add_i32 s21, 0, 0x10000
	s_and_b64 s[12:13], s[54:55], exec
	s_cselect_b32 s61, s47, s16
	s_cselect_b32 s60, s46, s11
	s_add_i32 s25, 0, 0x14000
	s_add_u32 s64, s14, 0x10080
	s_addc_u32 s65, s15, 0
	s_add_i32 s19, s21, s3
	s_add_i32 m0, s26, 0xc000
	s_add_i32 s28, s26, 0xe000
	s_add_i32 s15, s19, 0x2000
	v_add_u32_e32 v146, s21, v148
	s_add_u32 s62, s60, 0x10000
	ds_read_b128 v[152:155], v146
	ds_read_b128 v[156:159], v146 offset:1024
	ds_read_b128 v[160:163], v146 offset:2048
	ds_read_b128 v[164:167], v146 offset:3072
	v_add_u32_e32 v146, s25, v148
	s_addc_u32 s63, s61, 0
	s_add_i32 s17, s25, s3
	ds_read_b128 v[184:187], v146
	ds_read_b128 v[188:191], v146 offset:1024
	ds_read_b128 v[192:195], v146 offset:2048
	ds_read_b128 v[196:199], v146 offset:3072
	s_add_i32 s16, s17, 0x2000
	s_add_i32 s14, 0, 0x18000
	s_add_i32 s13, 0, 0x1c000
	s_add_u32 s56, s58, 0x10000
	s_addc_u32 s57, s59, 0
	s_add_i32 s12, s14, s3
	s_add_i32 s11, s12, 0x2000
	s_add_u32 s54, s60, 0x10080
	s_addc_u32 s55, s61, 0
	s_add_i32 s25, s13, s3
	s_add_i32 s21, s25, 0x2000
	v_lshl_add_u64 v[146:147], s[64:65], 0, v[144:145]
	ds_read_b128 v[200:203], v150
	ds_read_b128 v[204:207], v150 offset:1024
	ds_read_b128 v[208:211], v150 offset:2048
	ds_read_b128 v[212:215], v150 offset:3072
	ds_read_b128 v[216:219], v150 offset:4096
	ds_read_b128 v[220:223], v150 offset:5120
	ds_read_b128 v[224:227], v150 offset:6144
	ds_read_b128 v[228:231], v150 offset:7168
	global_load_lds_dwordx4 v[146:147], off
	v_lshl_add_u64 v[146:147], s[64:65], 0, v[140:141]
	s_mov_b32 m0, s28
	s_nop 0
	global_load_lds_dwordx4 v[146:147], off
	s_waitcnt vmcnt(8)
	s_waitcnt lgkmcnt(0)
	s_setprio 1
	s_barrier
	v_mfma_f32_16x16x32_bf16 v[124:127], v[152:155], v[200:203], v[124:127]
	v_mfma_f32_16x16x32_bf16 v[120:123], v[160:163], v[200:203], v[120:123]
	v_mfma_f32_16x16x32_bf16 v[112:115], v[152:155], v[208:211], v[112:115]
	v_mfma_f32_16x16x32_bf16 v[104:107], v[160:163], v[208:211], v[104:107]
	v_mfma_f32_16x16x32_bf16 v[96:99], v[152:155], v[216:219], v[96:99]
	v_mfma_f32_16x16x32_bf16 v[88:91], v[160:163], v[216:219], v[88:91]
	v_mfma_f32_16x16x32_bf16 v[80:83], v[152:155], v[224:227], v[80:83]
	v_mfma_f32_16x16x32_bf16 v[72:75], v[160:163], v[224:227], v[72:75]
	v_mfma_f32_16x16x32_bf16 v[124:127], v[156:159], v[204:207], v[124:127]
	v_mfma_f32_16x16x32_bf16 v[120:123], v[164:167], v[204:207], v[120:123]
	v_mfma_f32_16x16x32_bf16 v[112:115], v[156:159], v[212:215], v[112:115]
	v_mfma_f32_16x16x32_bf16 v[104:107], v[164:167], v[212:215], v[104:107]
	v_mfma_f32_16x16x32_bf16 v[96:99], v[156:159], v[220:223], v[96:99]
	v_mfma_f32_16x16x32_bf16 v[88:91], v[164:167], v[220:223], v[88:91]
	v_mfma_f32_16x16x32_bf16 v[80:83], v[156:159], v[228:231], v[80:83]
	v_mfma_f32_16x16x32_bf16 v[72:75], v[164:167], v[228:231], v[72:75]
	v_mfma_f32_16x16x32_bf16 v[116:119], v[184:187], v[200:203], v[116:119]
	v_mfma_f32_16x16x32_bf16 v[108:111], v[192:195], v[200:203], v[108:111]
	v_mfma_f32_16x16x32_bf16 v[100:103], v[184:187], v[208:211], v[100:103]
	v_mfma_f32_16x16x32_bf16 v[92:95], v[192:195], v[208:211], v[92:95]
	v_mfma_f32_16x16x32_bf16 v[84:87], v[184:187], v[216:219], v[84:87]
	v_mfma_f32_16x16x32_bf16 v[76:79], v[192:195], v[216:219], v[76:79]
	v_mfma_f32_16x16x32_bf16 v[68:71], v[184:187], v[224:227], v[68:71]
	v_mfma_f32_16x16x32_bf16 v[64:67], v[192:195], v[224:227], v[64:67]
	v_mfma_f32_16x16x32_bf16 v[116:119], v[188:191], v[204:207], v[116:119]
	v_mfma_f32_16x16x32_bf16 v[108:111], v[196:199], v[204:207], v[108:111]
	v_mfma_f32_16x16x32_bf16 v[100:103], v[188:191], v[212:215], v[100:103]
	v_mfma_f32_16x16x32_bf16 v[92:95], v[196:199], v[212:215], v[92:95]
	v_mfma_f32_16x16x32_bf16 v[84:87], v[188:191], v[220:223], v[84:87]
	v_mfma_f32_16x16x32_bf16 v[76:79], v[196:199], v[220:223], v[76:79]
	v_mfma_f32_16x16x32_bf16 v[68:71], v[188:191], v[228:231], v[68:71]
	v_mfma_f32_16x16x32_bf16 v[64:67], v[196:199], v[228:231], v[64:67]
	s_barrier
	s_setprio 0
	s_mov_b32 m0, s19
	v_lshl_add_u64 v[146:147], s[60:61], 0, v[142:143]
	ds_read_b128 v[200:203], v150 offset:16384
	ds_read_b128 v[204:207], v150 offset:17408
	ds_read_b128 v[208:211], v150 offset:18432
	ds_read_b128 v[212:215], v150 offset:19456
	ds_read_b128 v[216:219], v150 offset:20480
	ds_read_b128 v[220:223], v150 offset:21504
	ds_read_b128 v[224:227], v150 offset:22528
	ds_read_b128 v[228:231], v150 offset:23552
	global_load_lds_dwordx4 v[146:147], off
	v_lshl_add_u64 v[180:181], s[60:61], 0, v[138:139]
	s_mov_b32 m0, s15
	v_lshl_add_u64 v[182:183], s[62:63], 0, v[142:143]
	global_load_lds_dwordx4 v[180:181], off
	s_mov_b32 m0, s17
	v_lshl_add_u64 v[232:233], s[58:59], 0, v[140:141]
	global_load_lds_dwordx4 v[182:183], off
	v_lshl_add_u64 v[182:183], s[62:63], 0, v[138:139]
	s_mov_b32 m0, s16
	s_nop 0
	global_load_lds_dwordx4 v[182:183], off
	v_lshl_add_u64 v[182:183], s[58:59], 0, v[144:145]
	s_mov_b32 m0, s26
	s_nop 0
	global_load_lds_dwordx4 v[182:183], off
	s_mov_b32 m0, s27
	s_nop 0
	global_load_lds_dwordx4 v[232:233], off
	s_waitcnt vmcnt(8)
	s_waitcnt lgkmcnt(0)
	s_setprio 1
	s_barrier
; #define PG8_STAGE(bufoff, gbase, voff) do { _Pragma("unroll") for (int _i = 0; _i < 2; ++_i) \
;         __builtin_amdgcn_global_load_lds((const unsigned*)((const char*)(gbase) + (voff)[_i]), (LAS unsigned*)(lds + (bufoff) + ldsw + _i * 8192), 16, 0, 0); } while (0)
; #define PG8_LDA(dst, b, h) do { _Pragma("unroll") for (int m = 0; m < 4; ++m) _Pragma("unroll") for (int k = 0; k < 2; ++k) dst[m][k] = *(const LAS bf16x8*)(lds + PG8_SA(b, h) + aoff + m * 2048 + k * 1024); } while (0)
; #define PG8_LDB(dst, b, h) do { _Pragma("unroll") for (int n = 0; n < 2; ++n) _Pragma("unroll") for (int k = 0; k < 2; ++k) dst[n][k] = *(const LAS bf16x8*)(lds + PG8_SB(b, h) + boff + n * 2048 + k * 1024); } while (0)
; #define PG8_MMA(ai, bj, At, Bt) do { __builtin_amdgcn_s_setprio(1); _Pragma("unroll") for (int m = 0; m < 4; ++m) _Pragma("unroll") for (int n = 0; n < 2; ++n) _Pragma("unroll") for (int k = 0; k < 2; ++k) \
;         acc[ai][bj][m][n] = __builtin_amdgcn_mfma_f32_16x16x32_bf16(Bt[n][k], At[m][k], acc[ai][bj][m][n], 0, 0, 0); __builtin_amdgcn_s_setprio(0); } while (0)
; #define PG8_WAIT_V(n) asm volatile("s_waitcnt vmcnt(" #n ")" ::: "memory")
; #define PG8_WAIT_L(n) asm volatile("s_waitcnt lgkmcnt(" #n ")" ::: "memory")
; #define PG8_BAR __builtin_amdgcn_s_barrier()
; #define PG8_SCHED __builtin_amdgcn_sched_barrier(0)
; template <class Epi, class Sched>
; __device__ __forceinline__ void gemm_phase(LAS unsigned char* lds, const int K, const Sched& S, const Epi& E) {
;     ...
;             PG8_WAIT_V(8); PG8_WAIT_L(0); PG8_BAR; PG8_MMA(1, 0, At, B0); PG8_MMA(1, 1, At, B1); PG8_BAR; PG8_SCHED;
;             PG8_LDB(B0, 1, 0); PG8_LDB(B1, 1, 1); PG8_SCHED; PG8_LDA(At, 1, 0); PG8_STAGE(PG8_SA(0, 1), a2 + hstep, voffA);
;             PG8_WAIT_V(8); PG8_WAIT_L(0); PG8_BAR; PG8_MMA(0, 0, At, B0); PG8_MMA(0, 1, At, B1); PG8_BAR; PG8_SCHED;
	v_mfma_f32_16x16x32_bf16 v[60:63], v[152:155], v[200:203], v[60:63]
	v_mfma_f32_16x16x32_bf16 v[56:59], v[160:163], v[200:203], v[56:59]
	v_mfma_f32_16x16x32_bf16 v[48:51], v[152:155], v[208:211], v[48:51]
	v_mfma_f32_16x16x32_bf16 v[40:43], v[160:163], v[208:211], v[40:43]
	v_mfma_f32_16x16x32_bf16 v[32:35], v[152:155], v[216:219], v[32:35]
	v_mfma_f32_16x16x32_bf16 v[24:27], v[160:163], v[216:219], v[24:27]
	v_mfma_f32_16x16x32_bf16 v[16:19], v[152:155], v[224:227], v[16:19]
	v_mfma_f32_16x16x32_bf16 v[8:11], v[160:163], v[224:227], v[8:11]
	v_mfma_f32_16x16x32_bf16 v[60:63], v[156:159], v[204:207], v[60:63]
	v_mfma_f32_16x16x32_bf16 v[56:59], v[164:167], v[204:207], v[56:59]
	v_mfma_f32_16x16x32_bf16 v[48:51], v[156:159], v[212:215], v[48:51]
	v_mfma_f32_16x16x32_bf16 v[40:43], v[164:167], v[212:215], v[40:43]
	v_mfma_f32_16x16x32_bf16 v[32:35], v[156:159], v[220:223], v[32:35]
	v_mfma_f32_16x16x32_bf16 v[24:27], v[164:167], v[220:223], v[24:27]
	v_mfma_f32_16x16x32_bf16 v[16:19], v[156:159], v[228:231], v[16:19]
	v_mfma_f32_16x16x32_bf16 v[8:11], v[164:167], v[228:231], v[8:11]
	v_mfma_f32_16x16x32_bf16 v[52:55], v[184:187], v[200:203], v[52:55]
	v_mfma_f32_16x16x32_bf16 v[44:47], v[192:195], v[200:203], v[44:47]
	v_mfma_f32_16x16x32_bf16 v[36:39], v[184:187], v[208:211], v[36:39]
	v_mfma_f32_16x16x32_bf16 v[28:31], v[192:195], v[208:211], v[28:31]
	v_mfma_f32_16x16x32_bf16 v[20:23], v[184:187], v[216:219], v[20:23]
	v_mfma_f32_16x16x32_bf16 v[12:15], v[192:195], v[216:219], v[12:15]
	v_mfma_f32_16x16x32_bf16 v[4:7], v[184:187], v[224:227], v[4:7]
	v_mfma_f32_16x16x32_bf16 v[0:3], v[192:195], v[224:227], v[0:3]
	v_mfma_f32_16x16x32_bf16 v[52:55], v[188:191], v[204:207], v[52:55]
	v_mfma_f32_16x16x32_bf16 v[44:47], v[196:199], v[204:207], v[44:47]
	v_mfma_f32_16x16x32_bf16 v[36:39], v[188:191], v[212:215], v[36:39]
	v_mfma_f32_16x16x32_bf16 v[28:31], v[196:199], v[212:215], v[28:31]
	v_mfma_f32_16x16x32_bf16 v[20:23], v[188:191], v[220:223], v[20:23]
	v_mfma_f32_16x16x32_bf16 v[12:15], v[196:199], v[220:223], v[12:15]
	v_mfma_f32_16x16x32_bf16 v[4:7], v[188:191], v[228:231], v[4:7]
	v_mfma_f32_16x16x32_bf16 v[0:3], v[196:199], v[228:231], v[0:3]
	s_barrier
	s_setprio 0
	v_add_u32_e32 v151, s14, v148
	ds_read_b128 v[152:155], v151
	ds_read_b128 v[156:159], v151 offset:1024
	ds_read_b128 v[160:163], v151 offset:2048
	ds_read_b128 v[164:167], v151 offset:3072
	v_add_u32_e32 v151, s13, v148
	ds_read_b128 v[184:187], v151
	ds_read_b128 v[188:191], v151 offset:1024
	ds_read_b128 v[192:195], v151 offset:2048
	ds_read_b128 v[196:199], v151 offset:3072
	s_mov_b32 m0, s66
	v_lshl_add_u64 v[234:235], s[56:57], 0, v[144:145]
	ds_read_b128 v[200:203], v150 offset:32768
	ds_read_b128 v[204:207], v150 offset:33792
	ds_read_b128 v[208:211], v150 offset:34816
	ds_read_b128 v[212:215], v150 offset:35840
	ds_read_b128 v[216:219], v150 offset:36864
	ds_read_b128 v[220:223], v150 offset:37888
	ds_read_b128 v[224:227], v150 offset:38912
	ds_read_b128 v[228:231], v150 offset:39936
	global_load_lds_dwordx4 v[234:235], off
	v_lshl_add_u64 v[234:235], s[56:57], 0, v[140:141]
	s_mov_b32 m0, s67
	s_nop 0
	global_load_lds_dwordx4 v[234:235], off
	s_waitcnt vmcnt(8)
	s_waitcnt lgkmcnt(0)
	s_setprio 1
	s_barrier
	v_mfma_f32_16x16x32_bf16 v[124:127], v[152:155], v[200:203], v[124:127]
	v_mfma_f32_16x16x32_bf16 v[120:123], v[160:163], v[200:203], v[120:123]
	v_mfma_f32_16x16x32_bf16 v[112:115], v[152:155], v[208:211], v[112:115]
	v_mfma_f32_16x16x32_bf16 v[104:107], v[160:163], v[208:211], v[104:107]
	v_mfma_f32_16x16x32_bf16 v[96:99], v[152:155], v[216:219], v[96:99]
	v_mfma_f32_16x16x32_bf16 v[88:91], v[160:163], v[216:219], v[88:91]
	v_mfma_f32_16x16x32_bf16 v[80:83], v[152:155], v[224:227], v[80:83]
	v_mfma_f32_16x16x32_bf16 v[72:75], v[160:163], v[224:227], v[72:75]
	v_mfma_f32_16x16x32_bf16 v[124:127], v[156:159], v[204:207], v[124:127]
	v_mfma_f32_16x16x32_bf16 v[120:123], v[164:167], v[204:207], v[120:123]
	v_mfma_f32_16x16x32_bf16 v[112:115], v[156:159], v[212:215], v[112:115]
	v_mfma_f32_16x16x32_bf16 v[104:107], v[164:167], v[212:215], v[104:107]
	v_mfma_f32_16x16x32_bf16 v[96:99], v[156:159], v[220:223], v[96:99]
	v_mfma_f32_16x16x32_bf16 v[88:91], v[164:167], v[220:223], v[88:91]
	v_mfma_f32_16x16x32_bf16 v[80:83], v[156:159], v[228:231], v[80:83]
	v_mfma_f32_16x16x32_bf16 v[72:75], v[164:167], v[228:231], v[72:75]
	v_mfma_f32_16x16x32_bf16 v[116:119], v[184:187], v[200:203], v[116:119]
	v_mfma_f32_16x16x32_bf16 v[108:111], v[192:195], v[200:203], v[108:111]
	v_mfma_f32_16x16x32_bf16 v[100:103], v[184:187], v[208:211], v[100:103]
	v_mfma_f32_16x16x32_bf16 v[92:95], v[192:195], v[208:211], v[92:95]
	v_mfma_f32_16x16x32_bf16 v[84:87], v[184:187], v[216:219], v[84:87]
	v_mfma_f32_16x16x32_bf16 v[76:79], v[192:195], v[216:219], v[76:79]
	v_mfma_f32_16x16x32_bf16 v[68:71], v[184:187], v[224:227], v[68:71]
	v_mfma_f32_16x16x32_bf16 v[64:67], v[192:195], v[224:227], v[64:67]
	v_mfma_f32_16x16x32_bf16 v[116:119], v[188:191], v[204:207], v[116:119]
	v_mfma_f32_16x16x32_bf16 v[108:111], v[196:199], v[204:207], v[108:111]
	v_mfma_f32_16x16x32_bf16 v[100:103], v[188:191], v[212:215], v[100:103]
	v_mfma_f32_16x16x32_bf16 v[92:95], v[196:199], v[212:215], v[92:95]
	v_mfma_f32_16x16x32_bf16 v[84:87], v[188:191], v[220:223], v[84:87]
	v_mfma_f32_16x16x32_bf16 v[76:79], v[196:199], v[220:223], v[76:79]
	v_mfma_f32_16x16x32_bf16 v[68:71], v[188:191], v[228:231], v[68:71]
	v_mfma_f32_16x16x32_bf16 v[64:67], v[196:199], v[228:231], v[64:67]
	s_barrier
; #define PG8_STAGE(bufoff, gbase, voff) do { _Pragma("unroll") for (int _i = 0; _i < 2; ++_i) \
;         __builtin_amdgcn_global_load_lds((const unsigned*)((const char*)(gbase) + (voff)[_i]), (LAS unsigned*)(lds + (bufoff) + ldsw + _i * 8192), 16, 0, 0); } while (0)
; #define PG8_LDA(dst, b, h) do { _Pragma("unroll") for (int m = 0; m < 4; ++m) _Pragma("unroll") for (int k = 0; k < 2; ++k) dst[m][k] = *(const LAS bf16x8*)(lds + PG8_SA(b, h) + aoff + m * 2048 + k * 1024); } while (0)
; #define PG8_MMA(ai, bj, At, Bt) do { __builtin_amdgcn_s_setprio(1); _Pragma("unroll") for (int m = 0; m < 4; ++m) _Pragma("unroll") for (int n = 0; n < 2; ++n) _Pragma("unroll") for (int k = 0; k < 2; ++k) \
;         acc[ai][bj][m][n] = __builtin_amdgcn_mfma_f32_16x16x32_bf16(Bt[n][k], At[m][k], acc[ai][bj][m][n], 0, 0, 0); __builtin_amdgcn_s_setprio(0); } while (0)
; #define PG8_WAIT_V(n) asm volatile("s_waitcnt vmcnt(" #n ")" ::: "memory")
; #define PG8_WAIT_L(n) asm volatile("s_waitcnt lgkmcnt(" #n ")" ::: "memory")
; #define PG8_BAR __builtin_amdgcn_s_barrier()
; #define PG8_SCHED __builtin_amdgcn_sched_barrier(0)
; template <class Epi, class Sched>
; __device__ __forceinline__ void gemm_phase(LAS unsigned char* lds, const int K, const Sched& S, const Epi& E) {
;     ...
;             PG8_LDA(At, 1, 1); PG8_STAGE(PG8_SB(1, 0), b3, voffB); PG8_STAGE(PG8_SB(1, 1), b3 + hstep, voffB); PG8_STAGE(PG8_SA(1, 0), a3, voffA);
;             PG8_WAIT_V(8); PG8_WAIT_L(0); PG8_BAR; PG8_MMA(1, 0, At, B0); PG8_MMA(1, 1, At, B1); PG8_BAR; PG8_SCHED;
;         }
;         if (wr == 0) PG8_BAR;
	s_setprio 0
	s_mov_b32 m0, s12
	v_lshl_add_u64 v[146:147], v[146:147], 0, s[36:37]
	ds_read_b128 v[200:203], v150 offset:49152
	ds_read_b128 v[204:207], v150 offset:50176
	ds_read_b128 v[208:211], v150 offset:51200
	ds_read_b128 v[212:215], v150 offset:52224
	ds_read_b128 v[216:219], v150 offset:53248
	ds_read_b128 v[220:223], v150 offset:54272
	ds_read_b128 v[224:227], v150 offset:55296
	ds_read_b128 v[228:231], v150 offset:56320
	global_load_lds_dwordx4 v[146:147], off
	v_lshl_add_u64 v[146:147], v[180:181], 0, s[36:37]
	s_mov_b32 m0, s11
	s_nop 0
	global_load_lds_dwordx4 v[146:147], off
	v_lshl_add_u64 v[146:147], s[54:55], 0, v[142:143]
	s_mov_b32 m0, s25
	s_nop 0
	global_load_lds_dwordx4 v[146:147], off
	v_lshl_add_u64 v[146:147], s[54:55], 0, v[138:139]
	s_mov_b32 m0, s21
	s_nop 0
	global_load_lds_dwordx4 v[146:147], off
	v_lshl_add_u64 v[146:147], v[182:183], 0, s[36:37]
	s_mov_b32 m0, s0
	s_nop 0
	global_load_lds_dwordx4 v[146:147], off
	v_lshl_add_u64 v[146:147], v[232:233], 0, s[36:37]
	s_mov_b32 m0, s1
	s_nop 0
	global_load_lds_dwordx4 v[146:147], off
	s_waitcnt vmcnt(8)
	s_waitcnt lgkmcnt(0)
	s_setprio 1
	s_barrier
	v_mfma_f32_16x16x32_bf16 v[60:63], v[152:155], v[200:203], v[60:63]
	v_mfma_f32_16x16x32_bf16 v[56:59], v[160:163], v[200:203], v[56:59]
	v_mfma_f32_16x16x32_bf16 v[48:51], v[152:155], v[208:211], v[48:51]
	v_mfma_f32_16x16x32_bf16 v[40:43], v[160:163], v[208:211], v[40:43]
	v_mfma_f32_16x16x32_bf16 v[32:35], v[152:155], v[216:219], v[32:35]
	v_mfma_f32_16x16x32_bf16 v[24:27], v[160:163], v[216:219], v[24:27]
	v_mfma_f32_16x16x32_bf16 v[16:19], v[152:155], v[224:227], v[16:19]
	v_mfma_f32_16x16x32_bf16 v[8:11], v[160:163], v[224:227], v[8:11]
	v_mfma_f32_16x16x32_bf16 v[60:63], v[156:159], v[204:207], v[60:63]
	v_mfma_f32_16x16x32_bf16 v[56:59], v[164:167], v[204:207], v[56:59]
	v_mfma_f32_16x16x32_bf16 v[48:51], v[156:159], v[212:215], v[48:51]
	v_mfma_f32_16x16x32_bf16 v[40:43], v[164:167], v[212:215], v[40:43]
	v_mfma_f32_16x16x32_bf16 v[32:35], v[156:159], v[220:223], v[32:35]
	v_mfma_f32_16x16x32_bf16 v[24:27], v[164:167], v[220:223], v[24:27]
	v_mfma_f32_16x16x32_bf16 v[16:19], v[156:159], v[228:231], v[16:19]
	v_mfma_f32_16x16x32_bf16 v[8:11], v[164:167], v[228:231], v[8:11]
	v_mfma_f32_16x16x32_bf16 v[52:55], v[184:187], v[200:203], v[52:55]
	v_mfma_f32_16x16x32_bf16 v[44:47], v[192:195], v[200:203], v[44:47]
	v_mfma_f32_16x16x32_bf16 v[36:39], v[184:187], v[208:211], v[36:39]
	v_mfma_f32_16x16x32_bf16 v[28:31], v[192:195], v[208:211], v[28:31]
	v_mfma_f32_16x16x32_bf16 v[20:23], v[184:187], v[216:219], v[20:23]
	v_mfma_f32_16x16x32_bf16 v[12:15], v[192:195], v[216:219], v[12:15]
	v_mfma_f32_16x16x32_bf16 v[4:7], v[184:187], v[224:227], v[4:7]
	v_mfma_f32_16x16x32_bf16 v[0:3], v[192:195], v[224:227], v[0:3]
	v_mfma_f32_16x16x32_bf16 v[52:55], v[188:191], v[204:207], v[52:55]
	v_mfma_f32_16x16x32_bf16 v[44:47], v[196:199], v[204:207], v[44:47]
	v_mfma_f32_16x16x32_bf16 v[36:39], v[188:191], v[212:215], v[36:39]
	v_mfma_f32_16x16x32_bf16 v[28:31], v[196:199], v[212:215], v[28:31]
	v_mfma_f32_16x16x32_bf16 v[20:23], v[188:191], v[220:223], v[20:23]
	v_mfma_f32_16x16x32_bf16 v[12:15], v[196:199], v[220:223], v[12:15]
	v_mfma_f32_16x16x32_bf16 v[4:7], v[188:191], v[228:231], v[4:7]
	v_mfma_f32_16x16x32_bf16 v[0:3], v[196:199], v[228:231], v[0:3]
	s_barrier
	s_setprio 0
	s_movk_i32 s11, 0x100
	s_andn2_b64 vcc, exec, s[52:53]
	s_mov_b64 s[54:55], -1
	s_mov_b64 s[52:53], 0
	s_cbranch_vccz .LBB0_533
	s_and_b64 vcc, exec, s[40:41]
	s_cbranch_vccz .LBB0_536
	s_barrier

; #define PG8_STAGE(bufoff, gbase, voff) do { _Pragma("unroll") for (int _i = 0; _i < 2; ++_i) \
;         __builtin_amdgcn_global_load_lds((const unsigned*)((const char*)(gbase) + (voff)[_i]), (LAS unsigned*)(lds + (bufoff) + ldsw + _i * 8192), 16, 0, 0); } while (0)
; #define PG8_LDA(dst, b, h) do { _Pragma("unroll") for (int m = 0; m < 4; ++m) _Pragma("unroll") for (int k = 0; k < 2; ++k) dst[m][k] = *(const LAS bf16x8*)(lds + PG8_SA(b, h) + aoff + m * 2048 + k * 1024); } while (0)
; #define PG8_LDB(dst, b, h) do { _Pragma("unroll") for (int n = 0; n < 2; ++n) _Pragma("unroll") for (int k = 0; k < 2; ++k) dst[n][k] = *(const LAS bf16x8*)(lds + PG8_SB(b, h) + boff + n * 2048 + k * 1024); } while (0)
; #define PG8_MMA(ai, bj, At, Bt) do { __builtin_amdgcn_s_setprio(1); _Pragma("unroll") for (int m = 0; m < 4; ++m) _Pragma("unroll") for (int n = 0; n < 2; ++n) _Pragma("unroll") for (int k = 0; k < 2; ++k) \
;         acc[ai][bj][m][n] = __builtin_amdgcn_mfma_f32_16x16x32_bf16(Bt[n][k], At[m][k], acc[ai][bj][m][n], 0, 0, 0); __builtin_amdgcn_s_setprio(0); } while (0)
; #define PG8_WAIT_V(n) asm volatile("s_waitcnt vmcnt(" #n ")" ::: "memory")
; #define PG8_WAIT_L(n) asm volatile("s_waitcnt lgkmcnt(" #n ")" ::: "memory")
; #define PG8_BAR __builtin_amdgcn_s_barrier()
; #define PG8_SCHED __builtin_amdgcn_sched_barrier(0)
; template <class Epi, class Sched>
; __device__ __forceinline__ void gemm_phase(LAS unsigned char* lds, const int K, const Sched& S, const Epi& E) {
;     ...
;         for (int t = 0; t < nt; t += 2) {
;             const bool last = (t == nt - 2);
;             const char* a1 = cA + (size_t)(t + 1) * kstep;
;             const char* a2 = last ? nA : cA + (size_t)(t + 2) * kstep; const char* b2 = last ? nB : cB + (size_t)(t + 2) * kstep;
;             const char* a3 = a2 + kstep; const char* b3 = b2 + kstep;
;             PG8_LDB(B0, 0, 0); PG8_LDB(B1, 0, 1); PG8_SCHED; PG8_LDA(At, 0, 0); PG8_STAGE(PG8_SA(1, 1), a1 + hstep, voffA);
;             PG8_WAIT_V(8); PG8_WAIT_L(0); PG8_BAR; PG8_MMA(0, 0, At, B0); PG8_MMA(0, 1, At, B1); PG8_BAR; PG8_SCHED;
;             PG8_LDA(At, 0, 1); PG8_STAGE(PG8_SB(0, 0), b2, voffB); PG8_STAGE(PG8_SB(0, 1), b2 + hstep, voffB); PG8_STAGE(PG8_SA(0, 0), a2, voffA);
;             PG8_WAIT_V(8); PG8_WAIT_L(0); PG8_BAR; PG8_MMA(1, 0, At, B0); PG8_MMA(1, 1, At, B1); PG8_BAR; PG8_SCHED;
.LBB0_812:
	s_add_i32 s16, s15, 2
	s_add_u32 s50, s8, 0x100
	s_addc_u32 s51, s9, 0
	s_add_i32 s17, 0, 0x10000
	s_cmp_eq_u32 s12, s15
	s_cselect_b32 s55, s4, s51
	s_cselect_b32 s54, s5, s50
	s_cselect_b32 s53, s10, s14
	s_cselect_b32 s52, s11, s13
	s_add_i32 s15, 0, 0x14000
	v_add_u32_e32 v158, s17, v164
	v_add_u32_e32 v162, s15, v164
	ds_read_b128 v[146:149], v158
	ds_read_b128 v[150:153], v158 offset:1024
	ds_read_b128 v[154:157], v158 offset:2048
	ds_read_b128 v[158:161], v158 offset:3072
	ds_read_b128 v[184:187], v162
	ds_read_b128 v[188:191], v162 offset:1024
	ds_read_b128 v[192:195], v162 offset:2048
	ds_read_b128 v[196:199], v162 offset:3072
	v_lshl_add_u64 v[162:163], s[8:9], 0, v[142:143]
	s_add_i32 m0, s26, 0xc000
	ds_read_b128 v[200:203], v166
	ds_read_b128 v[204:207], v166 offset:1024
	ds_read_b128 v[208:211], v166 offset:2048
	ds_read_b128 v[212:215], v166 offset:3072
	ds_read_b128 v[216:219], v166 offset:4096
	ds_read_b128 v[220:223], v166 offset:5120
	ds_read_b128 v[224:227], v166 offset:6144
	ds_read_b128 v[228:231], v166 offset:7168
	global_load_lds_dwordx4 v[162:163], off
	v_lshl_add_u64 v[162:163], s[8:9], 0, v[144:145]
	s_add_i32 m0, s26, 0xe000
	s_nop 0
	global_load_lds_dwordx4 v[162:163], off
	s_waitcnt vmcnt(8)
	s_waitcnt lgkmcnt(0)
	s_setprio 1
	s_barrier
	v_mfma_f32_16x16x32_bf16 v[124:127], v[146:149], v[200:203], v[124:127]
	v_mfma_f32_16x16x32_bf16 v[92:95], v[154:157], v[200:203], v[92:95]
	v_mfma_f32_16x16x32_bf16 v[120:123], v[146:149], v[208:211], v[120:123]
	v_mfma_f32_16x16x32_bf16 v[88:91], v[154:157], v[208:211], v[88:91]
	v_mfma_f32_16x16x32_bf16 v[116:119], v[146:149], v[216:219], v[116:119]
	v_mfma_f32_16x16x32_bf16 v[84:87], v[154:157], v[216:219], v[84:87]
	v_mfma_f32_16x16x32_bf16 v[112:115], v[146:149], v[224:227], v[112:115]
	v_mfma_f32_16x16x32_bf16 v[80:83], v[154:157], v[224:227], v[80:83]
	v_mfma_f32_16x16x32_bf16 v[124:127], v[150:153], v[204:207], v[124:127]
	v_mfma_f32_16x16x32_bf16 v[92:95], v[158:161], v[204:207], v[92:95]
	v_mfma_f32_16x16x32_bf16 v[120:123], v[150:153], v[212:215], v[120:123]
	v_mfma_f32_16x16x32_bf16 v[88:91], v[158:161], v[212:215], v[88:91]
	v_mfma_f32_16x16x32_bf16 v[116:119], v[150:153], v[220:223], v[116:119]
	v_mfma_f32_16x16x32_bf16 v[84:87], v[158:161], v[220:223], v[84:87]
	v_mfma_f32_16x16x32_bf16 v[112:115], v[150:153], v[228:231], v[112:115]
	v_mfma_f32_16x16x32_bf16 v[80:83], v[158:161], v[228:231], v[80:83]
	v_mfma_f32_16x16x32_bf16 v[64:67], v[184:187], v[200:203], v[64:67]
	v_mfma_f32_16x16x32_bf16 v[40:43], v[192:195], v[200:203], v[40:43]
	v_mfma_f32_16x16x32_bf16 v[56:59], v[184:187], v[208:211], v[56:59]
	v_mfma_f32_16x16x32_bf16 v[32:35], v[192:195], v[208:211], v[32:35]
	v_mfma_f32_16x16x32_bf16 v[52:55], v[184:187], v[216:219], v[52:55]
	v_mfma_f32_16x16x32_bf16 v[24:27], v[192:195], v[216:219], v[24:27]
	v_mfma_f32_16x16x32_bf16 v[48:51], v[184:187], v[224:227], v[48:51]
	v_mfma_f32_16x16x32_bf16 v[16:19], v[192:195], v[224:227], v[16:19]
	v_mfma_f32_16x16x32_bf16 v[64:67], v[188:191], v[204:207], v[64:67]
	v_mfma_f32_16x16x32_bf16 v[40:43], v[196:199], v[204:207], v[40:43]
	v_mfma_f32_16x16x32_bf16 v[56:59], v[188:191], v[212:215], v[56:59]
	v_mfma_f32_16x16x32_bf16 v[32:35], v[196:199], v[212:215], v[32:35]
	v_mfma_f32_16x16x32_bf16 v[52:55], v[188:191], v[220:223], v[52:55]
	v_mfma_f32_16x16x32_bf16 v[24:27], v[196:199], v[220:223], v[24:27]
	v_mfma_f32_16x16x32_bf16 v[48:51], v[188:191], v[228:231], v[48:51]
	v_mfma_f32_16x16x32_bf16 v[16:19], v[196:199], v[228:231], v[16:19]
	s_barrier
	s_setprio 0
	s_add_i32 s8, s17, s3
	v_lshl_add_u64 v[162:163], s[52:53], 0, v[128:129]
	s_mov_b32 m0, s8
	ds_read_b128 v[200:203], v166 offset:16384
	ds_read_b128 v[204:207], v166 offset:17408
	ds_read_b128 v[208:211], v166 offset:18432
	ds_read_b128 v[212:215], v166 offset:19456
	ds_read_b128 v[216:219], v166 offset:20480
	ds_read_b128 v[220:223], v166 offset:21504
	ds_read_b128 v[224:227], v166 offset:22528
	ds_read_b128 v[228:231], v166 offset:23552
	global_load_lds_dwordx4 v[162:163], off
	s_add_i32 m0, s8, 0x2000
	s_add_u32 s8, s52, 0x50000
	v_lshl_add_u64 v[180:181], s[52:53], 0, v[138:139]
	s_addc_u32 s9, s53, 0
	s_add_i32 s15, s15, s3
	global_load_lds_dwordx4 v[180:181], off
	v_lshl_add_u64 v[182:183], s[8:9], 0, v[128:129]
	s_mov_b32 m0, s15
	v_lshl_add_u64 v[232:233], s[54:55], 0, v[138:139]
	global_load_lds_dwordx4 v[182:183], off
	v_lshl_add_u64 v[182:183], s[8:9], 0, v[138:139]
	s_add_i32 m0, s15, 0x2000
	s_nop 0
	global_load_lds_dwordx4 v[182:183], off
	v_lshl_add_u64 v[182:183], s[54:55], 0, v[128:129]
	s_mov_b32 m0, s26
	s_nop 0
	global_load_lds_dwordx4 v[182:183], off
	s_mov_b32 m0, s27
	s_nop 0
	global_load_lds_dwordx4 v[232:233], off
	s_waitcnt vmcnt(8)
	s_waitcnt lgkmcnt(0)
	s_setprio 1
	s_barrier
; #define PG8_STAGE(bufoff, gbase, voff) do { _Pragma("unroll") for (int _i = 0; _i < 2; ++_i) \
;         __builtin_amdgcn_global_load_lds((const unsigned*)((const char*)(gbase) + (voff)[_i]), (LAS unsigned*)(lds + (bufoff) + ldsw + _i * 8192), 16, 0, 0); } while (0)
; #define PG8_LDA(dst, b, h) do { _Pragma("unroll") for (int m = 0; m < 4; ++m) _Pragma("unroll") for (int k = 0; k < 2; ++k) dst[m][k] = *(const LAS bf16x8*)(lds + PG8_SA(b, h) + aoff + m * 2048 + k * 1024); } while (0)
; #define PG8_LDB(dst, b, h) do { _Pragma("unroll") for (int n = 0; n < 2; ++n) _Pragma("unroll") for (int k = 0; k < 2; ++k) dst[n][k] = *(const LAS bf16x8*)(lds + PG8_SB(b, h) + boff + n * 2048 + k * 1024); } while (0)
; #define PG8_MMA(ai, bj, At, Bt) do { __builtin_amdgcn_s_setprio(1); _Pragma("unroll") for (int m = 0; m < 4; ++m) _Pragma("unroll") for (int n = 0; n < 2; ++n) _Pragma("unroll") for (int k = 0; k < 2; ++k) \
;         acc[ai][bj][m][n] = __builtin_amdgcn_mfma_f32_16x16x32_bf16(Bt[n][k], At[m][k], acc[ai][bj][m][n], 0, 0, 0); __builtin_amdgcn_s_setprio(0); } while (0)
; #define PG8_WAIT_V(n) asm volatile("s_waitcnt vmcnt(" #n ")" ::: "memory")
; #define PG8_WAIT_L(n) asm volatile("s_waitcnt lgkmcnt(" #n ")" ::: "memory")
; #define PG8_BAR __builtin_amdgcn_s_barrier()
; #define PG8_SCHED __builtin_amdgcn_sched_barrier(0)
; template <class Epi, class Sched>
; __device__ __forceinline__ void gemm_phase(LAS unsigned char* lds, const int K, const Sched& S, const Epi& E) {
;     ...
;             PG8_WAIT_V(8); PG8_WAIT_L(0); PG8_BAR; PG8_MMA(1, 0, At, B0); PG8_MMA(1, 1, At, B1); PG8_BAR; PG8_SCHED;
;             PG8_LDB(B0, 1, 0); PG8_LDB(B1, 1, 1); PG8_SCHED; PG8_LDA(At, 1, 0); PG8_STAGE(PG8_SA(0, 1), a2 + hstep, voffA);
;             PG8_WAIT_V(8); PG8_WAIT_L(0); PG8_BAR; PG8_MMA(0, 0, At, B0); PG8_MMA(0, 1, At, B1); PG8_BAR; PG8_SCHED;
	v_mfma_f32_16x16x32_bf16 v[108:111], v[146:149], v[200:203], v[108:111]
	v_mfma_f32_16x16x32_bf16 v[76:79], v[154:157], v[200:203], v[76:79]
	v_mfma_f32_16x16x32_bf16 v[104:107], v[146:149], v[208:211], v[104:107]
	v_mfma_f32_16x16x32_bf16 v[72:75], v[154:157], v[208:211], v[72:75]
	v_mfma_f32_16x16x32_bf16 v[100:103], v[146:149], v[216:219], v[100:103]
	v_mfma_f32_16x16x32_bf16 v[68:71], v[154:157], v[216:219], v[68:71]
	v_mfma_f32_16x16x32_bf16 v[96:99], v[146:149], v[224:227], v[96:99]
	v_mfma_f32_16x16x32_bf16 v[60:63], v[154:157], v[224:227], v[60:63]
	v_mfma_f32_16x16x32_bf16 v[108:111], v[150:153], v[204:207], v[108:111]
	v_mfma_f32_16x16x32_bf16 v[76:79], v[158:161], v[204:207], v[76:79]
	v_mfma_f32_16x16x32_bf16 v[104:107], v[150:153], v[212:215], v[104:107]
	v_mfma_f32_16x16x32_bf16 v[72:75], v[158:161], v[212:215], v[72:75]
	v_mfma_f32_16x16x32_bf16 v[100:103], v[150:153], v[220:223], v[100:103]
	v_mfma_f32_16x16x32_bf16 v[68:71], v[158:161], v[220:223], v[68:71]
	v_mfma_f32_16x16x32_bf16 v[96:99], v[150:153], v[228:231], v[96:99]
	v_mfma_f32_16x16x32_bf16 v[60:63], v[158:161], v[228:231], v[60:63]
	v_mfma_f32_16x16x32_bf16 v[44:47], v[184:187], v[200:203], v[44:47]
	v_mfma_f32_16x16x32_bf16 v[12:15], v[192:195], v[200:203], v[12:15]
	v_mfma_f32_16x16x32_bf16 v[36:39], v[184:187], v[208:211], v[36:39]
	v_mfma_f32_16x16x32_bf16 v[8:11], v[192:195], v[208:211], v[8:11]
	v_mfma_f32_16x16x32_bf16 v[28:31], v[184:187], v[216:219], v[28:31]
	v_mfma_f32_16x16x32_bf16 v[4:7], v[192:195], v[216:219], v[4:7]
	v_mfma_f32_16x16x32_bf16 v[20:23], v[184:187], v[224:227], v[20:23]
	v_mfma_f32_16x16x32_bf16 v[0:3], v[192:195], v[224:227], v[0:3]
	v_mfma_f32_16x16x32_bf16 v[44:47], v[188:191], v[204:207], v[44:47]
	v_mfma_f32_16x16x32_bf16 v[12:15], v[196:199], v[204:207], v[12:15]
	v_mfma_f32_16x16x32_bf16 v[36:39], v[188:191], v[212:215], v[36:39]
	v_mfma_f32_16x16x32_bf16 v[8:11], v[196:199], v[212:215], v[8:11]
	v_mfma_f32_16x16x32_bf16 v[28:31], v[188:191], v[220:223], v[28:31]
	v_mfma_f32_16x16x32_bf16 v[4:7], v[196:199], v[220:223], v[4:7]
	v_mfma_f32_16x16x32_bf16 v[20:23], v[188:191], v[228:231], v[20:23]
	v_mfma_f32_16x16x32_bf16 v[0:3], v[196:199], v[228:231], v[0:3]
	s_barrier
	s_setprio 0
	s_add_i32 s15, 0, 0x18000
	s_add_i32 s17, 0, 0x1c000
	v_add_u32_e32 v158, s15, v164
	v_add_u32_e32 v167, s17, v164
	ds_read_b128 v[146:149], v158
	ds_read_b128 v[150:153], v158 offset:1024
	ds_read_b128 v[154:157], v158 offset:2048
	ds_read_b128 v[158:161], v158 offset:3072
	ds_read_b128 v[184:187], v167
	ds_read_b128 v[188:191], v167 offset:1024
	ds_read_b128 v[192:195], v167 offset:2048
	ds_read_b128 v[196:199], v167 offset:3072
	s_add_u32 s8, s54, 0x50000
	s_addc_u32 s9, s55, 0
	s_mov_b32 m0, s56
	v_lshl_add_u64 v[234:235], s[8:9], 0, v[128:129]
	ds_read_b128 v[200:203], v166 offset:32768
	ds_read_b128 v[204:207], v166 offset:33792
	ds_read_b128 v[208:211], v166 offset:34816
	ds_read_b128 v[212:215], v166 offset:35840
	ds_read_b128 v[216:219], v166 offset:36864
	ds_read_b128 v[220:223], v166 offset:37888
	ds_read_b128 v[224:227], v166 offset:38912
	ds_read_b128 v[228:231], v166 offset:39936
	global_load_lds_dwordx4 v[234:235], off
	v_lshl_add_u64 v[234:235], s[8:9], 0, v[138:139]
	s_mov_b32 m0, s57
	s_nop 0
	global_load_lds_dwordx4 v[234:235], off
	s_waitcnt vmcnt(8)
	s_waitcnt lgkmcnt(0)
	s_setprio 1
	s_barrier
	v_mfma_f32_16x16x32_bf16 v[124:127], v[146:149], v[200:203], v[124:127]
	v_mfma_f32_16x16x32_bf16 v[92:95], v[154:157], v[200:203], v[92:95]
	v_mfma_f32_16x16x32_bf16 v[120:123], v[146:149], v[208:211], v[120:123]
	v_mfma_f32_16x16x32_bf16 v[88:91], v[154:157], v[208:211], v[88:91]
	v_mfma_f32_16x16x32_bf16 v[116:119], v[146:149], v[216:219], v[116:119]
	v_mfma_f32_16x16x32_bf16 v[84:87], v[154:157], v[216:219], v[84:87]
	v_mfma_f32_16x16x32_bf16 v[112:115], v[146:149], v[224:227], v[112:115]
	v_mfma_f32_16x16x32_bf16 v[80:83], v[154:157], v[224:227], v[80:83]
	v_mfma_f32_16x16x32_bf16 v[124:127], v[150:153], v[204:207], v[124:127]
	v_mfma_f32_16x16x32_bf16 v[92:95], v[158:161], v[204:207], v[92:95]
	v_mfma_f32_16x16x32_bf16 v[120:123], v[150:153], v[212:215], v[120:123]
	v_mfma_f32_16x16x32_bf16 v[88:91], v[158:161], v[212:215], v[88:91]
	v_mfma_f32_16x16x32_bf16 v[116:119], v[150:153], v[220:223], v[116:119]
	v_mfma_f32_16x16x32_bf16 v[84:87], v[158:161], v[220:223], v[84:87]
	v_mfma_f32_16x16x32_bf16 v[112:115], v[150:153], v[228:231], v[112:115]
	v_mfma_f32_16x16x32_bf16 v[80:83], v[158:161], v[228:231], v[80:83]
	v_mfma_f32_16x16x32_bf16 v[64:67], v[184:187], v[200:203], v[64:67]
	v_mfma_f32_16x16x32_bf16 v[40:43], v[192:195], v[200:203], v[40:43]
	v_mfma_f32_16x16x32_bf16 v[56:59], v[184:187], v[208:211], v[56:59]
	v_mfma_f32_16x16x32_bf16 v[32:35], v[192:195], v[208:211], v[32:35]
	v_mfma_f32_16x16x32_bf16 v[52:55], v[184:187], v[216:219], v[52:55]
	v_mfma_f32_16x16x32_bf16 v[24:27], v[192:195], v[216:219], v[24:27]
	v_mfma_f32_16x16x32_bf16 v[48:51], v[184:187], v[224:227], v[48:51]
	v_mfma_f32_16x16x32_bf16 v[16:19], v[192:195], v[224:227], v[16:19]
	v_mfma_f32_16x16x32_bf16 v[64:67], v[188:191], v[204:207], v[64:67]
	v_mfma_f32_16x16x32_bf16 v[40:43], v[196:199], v[204:207], v[40:43]
	v_mfma_f32_16x16x32_bf16 v[56:59], v[188:191], v[212:215], v[56:59]
	v_mfma_f32_16x16x32_bf16 v[32:35], v[196:199], v[212:215], v[32:35]
	v_mfma_f32_16x16x32_bf16 v[52:55], v[188:191], v[220:223], v[52:55]
	v_mfma_f32_16x16x32_bf16 v[24:27], v[196:199], v[220:223], v[24:27]
	v_mfma_f32_16x16x32_bf16 v[48:51], v[188:191], v[228:231], v[48:51]
	v_mfma_f32_16x16x32_bf16 v[16:19], v[196:199], v[228:231], v[16:19]
	s_barrier
; #define PG8_STAGE(bufoff, gbase, voff) do { _Pragma("unroll") for (int _i = 0; _i < 2; ++_i) \
;         __builtin_amdgcn_global_load_lds((const unsigned*)((const char*)(gbase) + (voff)[_i]), (LAS unsigned*)(lds + (bufoff) + ldsw + _i * 8192), 16, 0, 0); } while (0)
; #define PG8_LDA(dst, b, h) do { _Pragma("unroll") for (int m = 0; m < 4; ++m) _Pragma("unroll") for (int k = 0; k < 2; ++k) dst[m][k] = *(const LAS bf16x8*)(lds + PG8_SA(b, h) + aoff + m * 2048 + k * 1024); } while (0)
; #define PG8_MMA(ai, bj, At, Bt) do { __builtin_amdgcn_s_setprio(1); _Pragma("unroll") for (int m = 0; m < 4; ++m) _Pragma("unroll") for (int n = 0; n < 2; ++n) _Pragma("unroll") for (int k = 0; k < 2; ++k) \
;         acc[ai][bj][m][n] = __builtin_amdgcn_mfma_f32_16x16x32_bf16(Bt[n][k], At[m][k], acc[ai][bj][m][n], 0, 0, 0); __builtin_amdgcn_s_setprio(0); } while (0)
; #define PG8_WAIT_V(n) asm volatile("s_waitcnt vmcnt(" #n ")" ::: "memory")
; #define PG8_WAIT_L(n) asm volatile("s_waitcnt lgkmcnt(" #n ")" ::: "memory")
; #define PG8_BAR __builtin_amdgcn_s_barrier()
; #define PG8_SCHED __builtin_amdgcn_sched_barrier(0)
; template <class Epi, class Sched>
; __device__ __forceinline__ void gemm_phase(LAS unsigned char* lds, const int K, const Sched& S, const Epi& E) {
;     ...
;             PG8_LDA(At, 1, 1); PG8_STAGE(PG8_SB(1, 0), b3, voffB); PG8_STAGE(PG8_SB(1, 1), b3 + hstep, voffB); PG8_STAGE(PG8_SA(1, 0), a3, voffA);
;             PG8_WAIT_V(8); PG8_WAIT_L(0); PG8_BAR; PG8_MMA(1, 0, At, B0); PG8_MMA(1, 1, At, B1); PG8_BAR; PG8_SCHED;
;         }
;         if (wr == 0) PG8_BAR;
	s_setprio 0
	s_add_i32 s8, s15, s3
	v_lshl_add_u64 v[162:163], v[162:163], 0, s[36:37]
	s_mov_b32 m0, s8
	ds_read_b128 v[200:203], v166 offset:49152
	ds_read_b128 v[204:207], v166 offset:50176
	ds_read_b128 v[208:211], v166 offset:51200
	ds_read_b128 v[212:215], v166 offset:52224
	ds_read_b128 v[216:219], v166 offset:53248
	ds_read_b128 v[220:223], v166 offset:54272
	ds_read_b128 v[224:227], v166 offset:55296
	ds_read_b128 v[228:231], v166 offset:56320
	global_load_lds_dwordx4 v[162:163], off
	s_add_i32 m0, s8, 0x2000
	s_add_u32 s8, s52, 0x50080
	v_lshl_add_u64 v[162:163], v[180:181], 0, s[36:37]
	s_addc_u32 s9, s53, 0
	s_add_i32 s15, s17, s3
	global_load_lds_dwordx4 v[162:163], off
	v_lshl_add_u64 v[162:163], s[8:9], 0, v[128:129]
	s_mov_b32 m0, s15
	s_nop 0
	global_load_lds_dwordx4 v[162:163], off
	v_lshl_add_u64 v[162:163], s[8:9], 0, v[138:139]
	s_add_i32 m0, s15, 0x2000
	s_nop 0
	global_load_lds_dwordx4 v[162:163], off
	v_lshl_add_u64 v[162:163], v[182:183], 0, s[36:37]
	s_mov_b32 m0, s58
	s_nop 0
	global_load_lds_dwordx4 v[162:163], off
	v_lshl_add_u64 v[162:163], v[232:233], 0, s[36:37]
	s_mov_b32 m0, s59
	s_nop 0
	global_load_lds_dwordx4 v[162:163], off
	s_waitcnt vmcnt(8)
	s_waitcnt lgkmcnt(0)
	s_setprio 1
	s_barrier
	v_mfma_f32_16x16x32_bf16 v[108:111], v[146:149], v[200:203], v[108:111]
	v_mfma_f32_16x16x32_bf16 v[76:79], v[154:157], v[200:203], v[76:79]
	v_mfma_f32_16x16x32_bf16 v[104:107], v[146:149], v[208:211], v[104:107]
	v_mfma_f32_16x16x32_bf16 v[72:75], v[154:157], v[208:211], v[72:75]
	v_mfma_f32_16x16x32_bf16 v[100:103], v[146:149], v[216:219], v[100:103]
	v_mfma_f32_16x16x32_bf16 v[68:71], v[154:157], v[216:219], v[68:71]
	v_mfma_f32_16x16x32_bf16 v[96:99], v[146:149], v[224:227], v[96:99]
	v_mfma_f32_16x16x32_bf16 v[60:63], v[154:157], v[224:227], v[60:63]
	v_mfma_f32_16x16x32_bf16 v[108:111], v[150:153], v[204:207], v[108:111]
	v_mfma_f32_16x16x32_bf16 v[76:79], v[158:161], v[204:207], v[76:79]
	v_mfma_f32_16x16x32_bf16 v[104:107], v[150:153], v[212:215], v[104:107]
	v_mfma_f32_16x16x32_bf16 v[72:75], v[158:161], v[212:215], v[72:75]
	v_mfma_f32_16x16x32_bf16 v[100:103], v[150:153], v[220:223], v[100:103]
	v_mfma_f32_16x16x32_bf16 v[68:71], v[158:161], v[220:223], v[68:71]
	v_mfma_f32_16x16x32_bf16 v[96:99], v[150:153], v[228:231], v[96:99]
	v_mfma_f32_16x16x32_bf16 v[60:63], v[158:161], v[228:231], v[60:63]
	v_mfma_f32_16x16x32_bf16 v[44:47], v[184:187], v[200:203], v[44:47]
	v_mfma_f32_16x16x32_bf16 v[12:15], v[192:195], v[200:203], v[12:15]
	v_mfma_f32_16x16x32_bf16 v[36:39], v[184:187], v[208:211], v[36:39]
	v_mfma_f32_16x16x32_bf16 v[8:11], v[192:195], v[208:211], v[8:11]
	v_mfma_f32_16x16x32_bf16 v[28:31], v[184:187], v[216:219], v[28:31]
	v_mfma_f32_16x16x32_bf16 v[4:7], v[192:195], v[216:219], v[4:7]
	v_mfma_f32_16x16x32_bf16 v[20:23], v[184:187], v[224:227], v[20:23]
	v_mfma_f32_16x16x32_bf16 v[0:3], v[192:195], v[224:227], v[0:3]
	v_mfma_f32_16x16x32_bf16 v[44:47], v[188:191], v[204:207], v[44:47]
	v_mfma_f32_16x16x32_bf16 v[12:15], v[196:199], v[204:207], v[12:15]
	v_mfma_f32_16x16x32_bf16 v[36:39], v[188:191], v[212:215], v[36:39]
	v_mfma_f32_16x16x32_bf16 v[8:11], v[196:199], v[212:215], v[8:11]
	v_mfma_f32_16x16x32_bf16 v[28:31], v[188:191], v[220:223], v[28:31]
	v_mfma_f32_16x16x32_bf16 v[4:7], v[196:199], v[220:223], v[4:7]
	v_mfma_f32_16x16x32_bf16 v[20:23], v[188:191], v[228:231], v[20:23]
	v_mfma_f32_16x16x32_bf16 v[0:3], v[196:199], v[228:231], v[0:3]
	s_barrier
	s_setprio 0
	s_add_u32 s13, s13, 0x100
	s_addc_u32 s14, s14, 0
	s_cmp_ge_i32 s16, s2
	s_mov_b64 s[8:9], s[50:51]
	s_mov_b32 s15, s16
	s_cbranch_scc0 .LBB0_812
	s_and_b64 vcc, exec, s[40:41]
	s_cbranch_vccz .LBB0_815
	s_barrier

; #define PG8_STAGE(bufoff, gbase, voff) do { _Pragma("unroll") for (int _i = 0; _i < 2; ++_i) \
;         __builtin_amdgcn_global_load_lds((const unsigned*)((const char*)(gbase) + (voff)[_i]), (LAS unsigned*)(lds + (bufoff) + ldsw + _i * 8192), 16, 0, 0); } while (0)
; #define PG8_LDA(dst, b, h) do { _Pragma("unroll") for (int m = 0; m < 4; ++m) _Pragma("unroll") for (int k = 0; k < 2; ++k) dst[m][k] = *(const LAS bf16x8*)(lds + PG8_SA(b, h) + aoff + m * 2048 + k * 1024); } while (0)
; #define PG8_LDB(dst, b, h) do { _Pragma("unroll") for (int n = 0; n < 2; ++n) _Pragma("unroll") for (int k = 0; k < 2; ++k) dst[n][k] = *(const LAS bf16x8*)(lds + PG8_SB(b, h) + boff + n * 2048 + k * 1024); } while (0)
; #define PG8_MMA(ai, bj, At, Bt) do { __builtin_amdgcn_s_setprio(1); _Pragma("unroll") for (int m = 0; m < 4; ++m) _Pragma("unroll") for (int n = 0; n < 2; ++n) _Pragma("unroll") for (int k = 0; k < 2; ++k) \
;         acc[ai][bj][m][n] = __builtin_amdgcn_mfma_f32_16x16x32_bf16(Bt[n][k], At[m][k], acc[ai][bj][m][n], 0, 0, 0); __builtin_amdgcn_s_setprio(0); } while (0)
; #define PG8_WAIT_V(n) asm volatile("s_waitcnt vmcnt(" #n ")" ::: "memory")
; #define PG8_WAIT_L(n) asm volatile("s_waitcnt lgkmcnt(" #n ")" ::: "memory")
; #define PG8_BAR __builtin_amdgcn_s_barrier()
; #define PG8_SCHED __builtin_amdgcn_sched_barrier(0)
; template <class Epi, class Sched>
; __device__ __forceinline__ void gemm_phase(LAS unsigned char* lds, const int K, const Sched& S, const Epi& E) {
;     ...
;         for (int t = 0; t < nt; t += 2) {
;             const bool last = (t == nt - 2);
;             const char* a1 = cA + (size_t)(t + 1) * kstep;
;             const char* a2 = last ? nA : cA + (size_t)(t + 2) * kstep; const char* b2 = last ? nB : cB + (size_t)(t + 2) * kstep;
;             const char* a3 = a2 + kstep; const char* b3 = b2 + kstep;
;             PG8_LDB(B0, 0, 0); PG8_LDB(B1, 0, 1); PG8_SCHED; PG8_LDA(At, 0, 0); PG8_STAGE(PG8_SA(1, 1), a1 + hstep, voffA);
;             PG8_WAIT_V(8); PG8_WAIT_L(0); PG8_BAR; PG8_MMA(0, 0, At, B0); PG8_MMA(0, 1, At, B1); PG8_BAR; PG8_SCHED;
;             PG8_LDA(At, 0, 1); PG8_STAGE(PG8_SB(0, 0), b2, voffB); PG8_STAGE(PG8_SB(0, 1), b2 + hstep, voffB); PG8_STAGE(PG8_SA(0, 0), a2, voffA);
;             PG8_WAIT_V(8); PG8_WAIT_L(0); PG8_BAR; PG8_MMA(1, 0, At, B0); PG8_MMA(1, 1, At, B1); PG8_BAR; PG8_SCHED;
.LBB0_963:
	s_add_u32 s5, s56, 0xfffc0080
	s_addc_u32 s9, s57, -1
	s_add_i32 s10, 0, 0x10000
	s_cmp_eq_u32 s4, 12
	s_cselect_b32 s61, s53, s9
	s_cselect_b32 s60, s52, s5
	v_add_u32_e32 v150, s10, v153
	s_cselect_b32 s59, s55, s2
	s_cselect_b32 s58, s54, s1
	s_add_i32 s5, 0, 0x14000
	ds_read_b128 v[156:159], v150
	ds_read_b128 v[160:163], v150 offset:1024
	ds_read_b128 v[164:167], v150 offset:2048
	ds_read_b128 v[180:183], v150 offset:3072
	v_add_u32_e32 v150, s5, v153
	ds_read_b128 v[184:187], v150
	ds_read_b128 v[188:191], v150 offset:1024
	ds_read_b128 v[192:195], v150 offset:2048
	ds_read_b128 v[196:199], v150 offset:3072
	v_lshl_add_u64 v[150:151], s[56:57], 0, v[146:147]
	s_add_i32 m0, s66, 0xc000
	ds_read_b128 v[200:203], v154
	ds_read_b128 v[204:207], v154 offset:1024
	ds_read_b128 v[208:211], v154 offset:2048
	ds_read_b128 v[212:215], v154 offset:3072
	ds_read_b128 v[216:219], v154 offset:4096
	ds_read_b128 v[220:223], v154 offset:5120
	ds_read_b128 v[224:227], v154 offset:6144
	ds_read_b128 v[228:231], v154 offset:7168
	global_load_lds_dwordx4 v[150:151], off
	v_lshl_add_u64 v[150:151], s[56:57], 0, v[148:149]
	s_add_i32 m0, s66, 0xe000
	s_nop 0
	global_load_lds_dwordx4 v[150:151], off
	s_waitcnt vmcnt(8)
	s_waitcnt lgkmcnt(0)
	s_setprio 1
	s_barrier
	v_mfma_f32_16x16x32_bf16 v[124:127], v[156:159], v[200:203], v[124:127]
	v_mfma_f32_16x16x32_bf16 v[116:119], v[164:167], v[200:203], v[116:119]
	v_mfma_f32_16x16x32_bf16 v[108:111], v[156:159], v[208:211], v[108:111]
	v_mfma_f32_16x16x32_bf16 v[100:103], v[164:167], v[208:211], v[100:103]
	v_mfma_f32_16x16x32_bf16 v[92:95], v[156:159], v[216:219], v[92:95]
	v_mfma_f32_16x16x32_bf16 v[84:87], v[164:167], v[216:219], v[84:87]
	v_mfma_f32_16x16x32_bf16 v[76:79], v[156:159], v[224:227], v[76:79]
	v_mfma_f32_16x16x32_bf16 v[68:71], v[164:167], v[224:227], v[68:71]
	v_mfma_f32_16x16x32_bf16 v[124:127], v[160:163], v[204:207], v[124:127]
	v_mfma_f32_16x16x32_bf16 v[116:119], v[180:183], v[204:207], v[116:119]
	v_mfma_f32_16x16x32_bf16 v[108:111], v[160:163], v[212:215], v[108:111]
	v_mfma_f32_16x16x32_bf16 v[100:103], v[180:183], v[212:215], v[100:103]
	v_mfma_f32_16x16x32_bf16 v[92:95], v[160:163], v[220:223], v[92:95]
	v_mfma_f32_16x16x32_bf16 v[84:87], v[180:183], v[220:223], v[84:87]
	v_mfma_f32_16x16x32_bf16 v[76:79], v[160:163], v[228:231], v[76:79]
	v_mfma_f32_16x16x32_bf16 v[68:71], v[180:183], v[228:231], v[68:71]
	v_mfma_f32_16x16x32_bf16 v[120:123], v[184:187], v[200:203], v[120:123]
	v_mfma_f32_16x16x32_bf16 v[112:115], v[192:195], v[200:203], v[112:115]
	v_mfma_f32_16x16x32_bf16 v[104:107], v[184:187], v[208:211], v[104:107]
	v_mfma_f32_16x16x32_bf16 v[96:99], v[192:195], v[208:211], v[96:99]
	v_mfma_f32_16x16x32_bf16 v[88:91], v[184:187], v[216:219], v[88:91]
	v_mfma_f32_16x16x32_bf16 v[80:83], v[192:195], v[216:219], v[80:83]
	v_mfma_f32_16x16x32_bf16 v[72:75], v[184:187], v[224:227], v[72:75]
	v_mfma_f32_16x16x32_bf16 v[64:67], v[192:195], v[224:227], v[64:67]
	v_mfma_f32_16x16x32_bf16 v[120:123], v[188:191], v[204:207], v[120:123]
	v_mfma_f32_16x16x32_bf16 v[112:115], v[196:199], v[204:207], v[112:115]
	v_mfma_f32_16x16x32_bf16 v[104:107], v[188:191], v[212:215], v[104:107]
	v_mfma_f32_16x16x32_bf16 v[96:99], v[196:199], v[212:215], v[96:99]
	v_mfma_f32_16x16x32_bf16 v[88:91], v[188:191], v[220:223], v[88:91]
	v_mfma_f32_16x16x32_bf16 v[80:83], v[196:199], v[220:223], v[80:83]
	v_mfma_f32_16x16x32_bf16 v[72:75], v[188:191], v[228:231], v[72:75]
	v_mfma_f32_16x16x32_bf16 v[64:67], v[196:199], v[228:231], v[64:67]
	s_barrier
	s_setprio 0
	s_add_i32 s9, s10, s63
	v_lshl_add_u64 v[150:151], s[58:59], 0, v[142:143]
	s_mov_b32 m0, s9
	ds_read_b128 v[200:203], v154 offset:16384
	ds_read_b128 v[204:207], v154 offset:17408
	ds_read_b128 v[208:211], v154 offset:18432
	ds_read_b128 v[212:215], v154 offset:19456
	ds_read_b128 v[216:219], v154 offset:20480
	ds_read_b128 v[220:223], v154 offset:21504
	ds_read_b128 v[224:227], v154 offset:22528
	ds_read_b128 v[228:231], v154 offset:23552
	global_load_lds_dwordx4 v[150:151], off
	s_add_i32 m0, s9, 0x2000
	s_add_u32 s10, s58, 0x40000
	v_lshl_add_u64 v[232:233], s[58:59], 0, v[138:139]
	s_addc_u32 s11, s59, 0
	s_add_i32 s5, s5, s63
	global_load_lds_dwordx4 v[232:233], off
	v_lshl_add_u64 v[234:235], s[10:11], 0, v[142:143]
	s_mov_b32 m0, s5
	v_lshl_add_u64 v[236:237], s[60:61], 0, v[140:141]
	global_load_lds_dwordx4 v[234:235], off
	v_lshl_add_u64 v[234:235], s[10:11], 0, v[138:139]
	s_add_i32 m0, s5, 0x2000
	s_nop 0
	global_load_lds_dwordx4 v[234:235], off
	v_lshl_add_u64 v[234:235], s[60:61], 0, v[144:145]
	s_mov_b32 m0, s66
	s_nop 0
	global_load_lds_dwordx4 v[234:235], off
	s_mov_b32 m0, s67
	s_nop 0
	global_load_lds_dwordx4 v[236:237], off
	s_waitcnt vmcnt(8)
	s_waitcnt lgkmcnt(0)
	s_setprio 1
	s_barrier
; #define PG8_STAGE(bufoff, gbase, voff) do { _Pragma("unroll") for (int _i = 0; _i < 2; ++_i) \
;         __builtin_amdgcn_global_load_lds((const unsigned*)((const char*)(gbase) + (voff)[_i]), (LAS unsigned*)(lds + (bufoff) + ldsw + _i * 8192), 16, 0, 0); } while (0)
; #define PG8_LDA(dst, b, h) do { _Pragma("unroll") for (int m = 0; m < 4; ++m) _Pragma("unroll") for (int k = 0; k < 2; ++k) dst[m][k] = *(const LAS bf16x8*)(lds + PG8_SA(b, h) + aoff + m * 2048 + k * 1024); } while (0)
; #define PG8_LDB(dst, b, h) do { _Pragma("unroll") for (int n = 0; n < 2; ++n) _Pragma("unroll") for (int k = 0; k < 2; ++k) dst[n][k] = *(const LAS bf16x8*)(lds + PG8_SB(b, h) + boff + n * 2048 + k * 1024); } while (0)
; #define PG8_MMA(ai, bj, At, Bt) do { __builtin_amdgcn_s_setprio(1); _Pragma("unroll") for (int m = 0; m < 4; ++m) _Pragma("unroll") for (int n = 0; n < 2; ++n) _Pragma("unroll") for (int k = 0; k < 2; ++k) \
;         acc[ai][bj][m][n] = __builtin_amdgcn_mfma_f32_16x16x32_bf16(Bt[n][k], At[m][k], acc[ai][bj][m][n], 0, 0, 0); __builtin_amdgcn_s_setprio(0); } while (0)
; #define PG8_WAIT_V(n) asm volatile("s_waitcnt vmcnt(" #n ")" ::: "memory")
; #define PG8_WAIT_L(n) asm volatile("s_waitcnt lgkmcnt(" #n ")" ::: "memory")
; #define PG8_BAR __builtin_amdgcn_s_barrier()
; #define PG8_SCHED __builtin_amdgcn_sched_barrier(0)
; template <class Epi, class Sched>
; __device__ __forceinline__ void gemm_phase(LAS unsigned char* lds, const int K, const Sched& S, const Epi& E) {
;     ...
;             PG8_WAIT_V(8); PG8_WAIT_L(0); PG8_BAR; PG8_MMA(1, 0, At, B0); PG8_MMA(1, 1, At, B1); PG8_BAR; PG8_SCHED;
;             PG8_LDB(B0, 1, 0); PG8_LDB(B1, 1, 1); PG8_SCHED; PG8_LDA(At, 1, 0); PG8_STAGE(PG8_SA(0, 1), a2 + hstep, voffA);
;             PG8_WAIT_V(8); PG8_WAIT_L(0); PG8_BAR; PG8_MMA(0, 0, At, B0); PG8_MMA(0, 1, At, B1); PG8_BAR; PG8_SCHED;
	v_mfma_f32_16x16x32_bf16 v[60:63], v[156:159], v[200:203], v[60:63]
	v_mfma_f32_16x16x32_bf16 v[52:55], v[164:167], v[200:203], v[52:55]
	v_mfma_f32_16x16x32_bf16 v[44:47], v[156:159], v[208:211], v[44:47]
	v_mfma_f32_16x16x32_bf16 v[36:39], v[164:167], v[208:211], v[36:39]
	v_mfma_f32_16x16x32_bf16 v[28:31], v[156:159], v[216:219], v[28:31]
	v_mfma_f32_16x16x32_bf16 v[20:23], v[164:167], v[216:219], v[20:23]
	v_mfma_f32_16x16x32_bf16 v[12:15], v[156:159], v[224:227], v[12:15]
	v_mfma_f32_16x16x32_bf16 v[4:7], v[164:167], v[224:227], v[4:7]
	v_mfma_f32_16x16x32_bf16 v[60:63], v[160:163], v[204:207], v[60:63]
	v_mfma_f32_16x16x32_bf16 v[52:55], v[180:183], v[204:207], v[52:55]
	v_mfma_f32_16x16x32_bf16 v[44:47], v[160:163], v[212:215], v[44:47]
	v_mfma_f32_16x16x32_bf16 v[36:39], v[180:183], v[212:215], v[36:39]
	v_mfma_f32_16x16x32_bf16 v[28:31], v[160:163], v[220:223], v[28:31]
	v_mfma_f32_16x16x32_bf16 v[20:23], v[180:183], v[220:223], v[20:23]
	v_mfma_f32_16x16x32_bf16 v[12:15], v[160:163], v[228:231], v[12:15]
	v_mfma_f32_16x16x32_bf16 v[4:7], v[180:183], v[228:231], v[4:7]
	v_mfma_f32_16x16x32_bf16 v[56:59], v[184:187], v[200:203], v[56:59]
	v_mfma_f32_16x16x32_bf16 v[48:51], v[192:195], v[200:203], v[48:51]
	v_mfma_f32_16x16x32_bf16 v[40:43], v[184:187], v[208:211], v[40:43]
	v_mfma_f32_16x16x32_bf16 v[32:35], v[192:195], v[208:211], v[32:35]
	v_mfma_f32_16x16x32_bf16 v[24:27], v[184:187], v[216:219], v[24:27]
	v_mfma_f32_16x16x32_bf16 v[16:19], v[192:195], v[216:219], v[16:19]
	v_mfma_f32_16x16x32_bf16 v[8:11], v[184:187], v[224:227], v[8:11]
	v_mfma_f32_16x16x32_bf16 v[0:3], v[192:195], v[224:227], v[0:3]
	v_mfma_f32_16x16x32_bf16 v[56:59], v[188:191], v[204:207], v[56:59]
	v_mfma_f32_16x16x32_bf16 v[48:51], v[196:199], v[204:207], v[48:51]
	v_mfma_f32_16x16x32_bf16 v[40:43], v[188:191], v[212:215], v[40:43]
	v_mfma_f32_16x16x32_bf16 v[32:35], v[196:199], v[212:215], v[32:35]
	v_mfma_f32_16x16x32_bf16 v[24:27], v[188:191], v[220:223], v[24:27]
	v_mfma_f32_16x16x32_bf16 v[16:19], v[196:199], v[220:223], v[16:19]
	v_mfma_f32_16x16x32_bf16 v[8:11], v[188:191], v[228:231], v[8:11]
	v_mfma_f32_16x16x32_bf16 v[0:3], v[196:199], v[228:231], v[0:3]
	s_barrier
	s_setprio 0
	s_add_i32 s5, 0, 0x18000
	v_add_u32_e32 v155, s5, v153
	s_add_i32 s9, 0, 0x1c000
	ds_read_b128 v[156:159], v155
	ds_read_b128 v[160:163], v155 offset:1024
	ds_read_b128 v[164:167], v155 offset:2048
	ds_read_b128 v[180:183], v155 offset:3072
	v_add_u32_e32 v155, s9, v153
	ds_read_b128 v[184:187], v155
	ds_read_b128 v[188:191], v155 offset:1024
	ds_read_b128 v[192:195], v155 offset:2048
	ds_read_b128 v[196:199], v155 offset:3072
	s_add_u32 s10, s60, 0x40000
	s_addc_u32 s11, s61, 0
	s_mov_b32 m0, s68
	v_lshl_add_u64 v[238:239], s[10:11], 0, v[144:145]
	ds_read_b128 v[200:203], v154 offset:32768
	ds_read_b128 v[204:207], v154 offset:33792
	ds_read_b128 v[208:211], v154 offset:34816
	ds_read_b128 v[212:215], v154 offset:35840
	ds_read_b128 v[216:219], v154 offset:36864
	ds_read_b128 v[220:223], v154 offset:37888
	ds_read_b128 v[224:227], v154 offset:38912
	ds_read_b128 v[228:231], v154 offset:39936
	global_load_lds_dwordx4 v[238:239], off
	v_lshl_add_u64 v[238:239], s[10:11], 0, v[140:141]
	s_mov_b32 m0, s69
	s_nop 0
	global_load_lds_dwordx4 v[238:239], off
	s_waitcnt vmcnt(8)
	s_waitcnt lgkmcnt(0)
	s_setprio 1
	s_barrier
	v_mfma_f32_16x16x32_bf16 v[124:127], v[156:159], v[200:203], v[124:127]
	v_mfma_f32_16x16x32_bf16 v[116:119], v[164:167], v[200:203], v[116:119]
	v_mfma_f32_16x16x32_bf16 v[108:111], v[156:159], v[208:211], v[108:111]
	v_mfma_f32_16x16x32_bf16 v[100:103], v[164:167], v[208:211], v[100:103]
	v_mfma_f32_16x16x32_bf16 v[92:95], v[156:159], v[216:219], v[92:95]
	v_mfma_f32_16x16x32_bf16 v[84:87], v[164:167], v[216:219], v[84:87]
	v_mfma_f32_16x16x32_bf16 v[76:79], v[156:159], v[224:227], v[76:79]
	v_mfma_f32_16x16x32_bf16 v[68:71], v[164:167], v[224:227], v[68:71]
	v_mfma_f32_16x16x32_bf16 v[124:127], v[160:163], v[204:207], v[124:127]
	v_mfma_f32_16x16x32_bf16 v[116:119], v[180:183], v[204:207], v[116:119]
	v_mfma_f32_16x16x32_bf16 v[108:111], v[160:163], v[212:215], v[108:111]
	v_mfma_f32_16x16x32_bf16 v[100:103], v[180:183], v[212:215], v[100:103]
	v_mfma_f32_16x16x32_bf16 v[92:95], v[160:163], v[220:223], v[92:95]
	v_mfma_f32_16x16x32_bf16 v[84:87], v[180:183], v[220:223], v[84:87]
	v_mfma_f32_16x16x32_bf16 v[76:79], v[160:163], v[228:231], v[76:79]
	v_mfma_f32_16x16x32_bf16 v[68:71], v[180:183], v[228:231], v[68:71]
	v_mfma_f32_16x16x32_bf16 v[120:123], v[184:187], v[200:203], v[120:123]
	v_mfma_f32_16x16x32_bf16 v[112:115], v[192:195], v[200:203], v[112:115]
	v_mfma_f32_16x16x32_bf16 v[104:107], v[184:187], v[208:211], v[104:107]
	v_mfma_f32_16x16x32_bf16 v[96:99], v[192:195], v[208:211], v[96:99]
	v_mfma_f32_16x16x32_bf16 v[88:91], v[184:187], v[216:219], v[88:91]
	v_mfma_f32_16x16x32_bf16 v[80:83], v[192:195], v[216:219], v[80:83]
	v_mfma_f32_16x16x32_bf16 v[72:75], v[184:187], v[224:227], v[72:75]
	v_mfma_f32_16x16x32_bf16 v[64:67], v[192:195], v[224:227], v[64:67]
	v_mfma_f32_16x16x32_bf16 v[120:123], v[188:191], v[204:207], v[120:123]
	v_mfma_f32_16x16x32_bf16 v[112:115], v[196:199], v[204:207], v[112:115]
	v_mfma_f32_16x16x32_bf16 v[104:107], v[188:191], v[212:215], v[104:107]
	v_mfma_f32_16x16x32_bf16 v[96:99], v[196:199], v[212:215], v[96:99]
	v_mfma_f32_16x16x32_bf16 v[88:91], v[188:191], v[220:223], v[88:91]
	v_mfma_f32_16x16x32_bf16 v[80:83], v[196:199], v[220:223], v[80:83]
	v_mfma_f32_16x16x32_bf16 v[72:75], v[188:191], v[228:231], v[72:75]
	v_mfma_f32_16x16x32_bf16 v[64:67], v[196:199], v[228:231], v[64:67]
	s_barrier
; #define PG8_STAGE(bufoff, gbase, voff) do { _Pragma("unroll") for (int _i = 0; _i < 2; ++_i) \
;         __builtin_amdgcn_global_load_lds((const unsigned*)((const char*)(gbase) + (voff)[_i]), (LAS unsigned*)(lds + (bufoff) + ldsw + _i * 8192), 16, 0, 0); } while (0)
; #define PG8_LDA(dst, b, h) do { _Pragma("unroll") for (int m = 0; m < 4; ++m) _Pragma("unroll") for (int k = 0; k < 2; ++k) dst[m][k] = *(const LAS bf16x8*)(lds + PG8_SA(b, h) + aoff + m * 2048 + k * 1024); } while (0)
; #define PG8_MMA(ai, bj, At, Bt) do { __builtin_amdgcn_s_setprio(1); _Pragma("unroll") for (int m = 0; m < 4; ++m) _Pragma("unroll") for (int n = 0; n < 2; ++n) _Pragma("unroll") for (int k = 0; k < 2; ++k) \
;         acc[ai][bj][m][n] = __builtin_amdgcn_mfma_f32_16x16x32_bf16(Bt[n][k], At[m][k], acc[ai][bj][m][n], 0, 0, 0); __builtin_amdgcn_s_setprio(0); } while (0)
; #define PG8_WAIT_V(n) asm volatile("s_waitcnt vmcnt(" #n ")" ::: "memory")
; #define PG8_WAIT_L(n) asm volatile("s_waitcnt lgkmcnt(" #n ")" ::: "memory")
; #define PG8_BAR __builtin_amdgcn_s_barrier()
; #define PG8_SCHED __builtin_amdgcn_sched_barrier(0)
; template <class Epi, class Sched>
; __device__ __forceinline__ void gemm_phase(LAS unsigned char* lds, const int K, const Sched& S, const Epi& E) {
;     ...
;             PG8_LDA(At, 1, 1); PG8_STAGE(PG8_SB(1, 0), b3, voffB); PG8_STAGE(PG8_SB(1, 1), b3 + hstep, voffB); PG8_STAGE(PG8_SA(1, 0), a3, voffA);
;             PG8_WAIT_V(8); PG8_WAIT_L(0); PG8_BAR; PG8_MMA(1, 0, At, B0); PG8_MMA(1, 1, At, B1); PG8_BAR; PG8_SCHED;
;         }
;         if (wr == 0) PG8_BAR;
	s_setprio 0
	s_add_i32 s5, s5, s63
	v_lshl_add_u64 v[150:151], v[150:151], 0, s[36:37]
	s_mov_b32 m0, s5
	ds_read_b128 v[200:203], v154 offset:49152
	ds_read_b128 v[204:207], v154 offset:50176
	ds_read_b128 v[208:211], v154 offset:51200
	ds_read_b128 v[212:215], v154 offset:52224
	ds_read_b128 v[216:219], v154 offset:53248
	ds_read_b128 v[220:223], v154 offset:54272
	ds_read_b128 v[224:227], v154 offset:55296
	ds_read_b128 v[228:231], v154 offset:56320
	global_load_lds_dwordx4 v[150:151], off
	s_add_i32 m0, s5, 0x2000
	s_add_u32 s10, s58, 0x40080
	v_lshl_add_u64 v[150:151], v[232:233], 0, s[36:37]
	s_addc_u32 s11, s59, 0
	s_add_i32 s5, s9, s63
	global_load_lds_dwordx4 v[150:151], off
	v_lshl_add_u64 v[150:151], s[10:11], 0, v[142:143]
	s_mov_b32 m0, s5
	s_nop 0
	global_load_lds_dwordx4 v[150:151], off
	v_lshl_add_u64 v[150:151], s[10:11], 0, v[138:139]
	s_add_i32 m0, s5, 0x2000
	s_nop 0
	global_load_lds_dwordx4 v[150:151], off
	v_lshl_add_u64 v[150:151], v[234:235], 0, s[36:37]
	s_mov_b32 m0, s70
	s_nop 0
	global_load_lds_dwordx4 v[150:151], off
	v_lshl_add_u64 v[150:151], v[236:237], 0, s[36:37]
	s_mov_b32 m0, s71
	s_nop 0
	global_load_lds_dwordx4 v[150:151], off
	s_waitcnt vmcnt(8)
	s_waitcnt lgkmcnt(0)
	s_setprio 1
	s_barrier
	v_mfma_f32_16x16x32_bf16 v[60:63], v[156:159], v[200:203], v[60:63]
	v_mfma_f32_16x16x32_bf16 v[52:55], v[164:167], v[200:203], v[52:55]
	v_mfma_f32_16x16x32_bf16 v[44:47], v[156:159], v[208:211], v[44:47]
	v_mfma_f32_16x16x32_bf16 v[36:39], v[164:167], v[208:211], v[36:39]
	v_mfma_f32_16x16x32_bf16 v[28:31], v[156:159], v[216:219], v[28:31]
	v_mfma_f32_16x16x32_bf16 v[20:23], v[164:167], v[216:219], v[20:23]
	v_mfma_f32_16x16x32_bf16 v[12:15], v[156:159], v[224:227], v[12:15]
	v_mfma_f32_16x16x32_bf16 v[4:7], v[164:167], v[224:227], v[4:7]
	v_mfma_f32_16x16x32_bf16 v[60:63], v[160:163], v[204:207], v[60:63]
	v_mfma_f32_16x16x32_bf16 v[52:55], v[180:183], v[204:207], v[52:55]
	v_mfma_f32_16x16x32_bf16 v[44:47], v[160:163], v[212:215], v[44:47]
	v_mfma_f32_16x16x32_bf16 v[36:39], v[180:183], v[212:215], v[36:39]
	v_mfma_f32_16x16x32_bf16 v[28:31], v[160:163], v[220:223], v[28:31]
	v_mfma_f32_16x16x32_bf16 v[20:23], v[180:183], v[220:223], v[20:23]
	v_mfma_f32_16x16x32_bf16 v[12:15], v[160:163], v[228:231], v[12:15]
	v_mfma_f32_16x16x32_bf16 v[4:7], v[180:183], v[228:231], v[4:7]
	v_mfma_f32_16x16x32_bf16 v[56:59], v[184:187], v[200:203], v[56:59]
	v_mfma_f32_16x16x32_bf16 v[48:51], v[192:195], v[200:203], v[48:51]
	v_mfma_f32_16x16x32_bf16 v[40:43], v[184:187], v[208:211], v[40:43]
	v_mfma_f32_16x16x32_bf16 v[32:35], v[192:195], v[208:211], v[32:35]
	v_mfma_f32_16x16x32_bf16 v[24:27], v[184:187], v[216:219], v[24:27]
	v_mfma_f32_16x16x32_bf16 v[16:19], v[192:195], v[216:219], v[16:19]
	v_mfma_f32_16x16x32_bf16 v[8:11], v[184:187], v[224:227], v[8:11]
	v_mfma_f32_16x16x32_bf16 v[0:3], v[192:195], v[224:227], v[0:3]
	v_mfma_f32_16x16x32_bf16 v[56:59], v[188:191], v[204:207], v[56:59]
	v_mfma_f32_16x16x32_bf16 v[48:51], v[196:199], v[204:207], v[48:51]
	v_mfma_f32_16x16x32_bf16 v[40:43], v[188:191], v[212:215], v[40:43]
	v_mfma_f32_16x16x32_bf16 v[32:35], v[196:199], v[212:215], v[32:35]
	v_mfma_f32_16x16x32_bf16 v[24:27], v[188:191], v[220:223], v[24:27]
	v_mfma_f32_16x16x32_bf16 v[16:19], v[196:199], v[220:223], v[16:19]
	v_mfma_f32_16x16x32_bf16 v[8:11], v[188:191], v[228:231], v[8:11]
	v_mfma_f32_16x16x32_bf16 v[0:3], v[196:199], v[228:231], v[0:3]
	s_barrier
	s_setprio 0
	s_add_i32 s4, s4, 2
	s_add_u32 s56, s56, 0x100
	s_addc_u32 s57, s57, 0
	s_add_u32 s1, s1, 0x100
	s_addc_u32 s2, s2, 0
	s_cmp_gt_u32 s4, 13
	s_cbranch_scc0 .LBB0_963
	s_and_b64 vcc, exec, s[46:47]
	s_cbranch_vccz .LBB0_966
	s_barrier

; #define PG8_STAGE(bufoff, gbase, voff) do { _Pragma("unroll") for (int _i = 0; _i < 2; ++_i) \
;         __builtin_amdgcn_global_load_lds((const unsigned*)((const char*)(gbase) + (voff)[_i]), (LAS unsigned*)(lds + (bufoff) + ldsw + _i * 8192), 16, 0, 0); } while (0)
; #define PG8_LDA(dst, b, h) do { _Pragma("unroll") for (int m = 0; m < 4; ++m) _Pragma("unroll") for (int k = 0; k < 2; ++k) dst[m][k] = *(const LAS bf16x8*)(lds + PG8_SA(b, h) + aoff + m * 2048 + k * 1024); } while (0)
; #define PG8_LDB(dst, b, h) do { _Pragma("unroll") for (int n = 0; n < 2; ++n) _Pragma("unroll") for (int k = 0; k < 2; ++k) dst[n][k] = *(const LAS bf16x8*)(lds + PG8_SB(b, h) + boff + n * 2048 + k * 1024); } while (0)
; #define PG8_MMA(ai, bj, At, Bt) do { __builtin_amdgcn_s_setprio(1); _Pragma("unroll") for (int m = 0; m < 4; ++m) _Pragma("unroll") for (int n = 0; n < 2; ++n) _Pragma("unroll") for (int k = 0; k < 2; ++k) \
;         acc[ai][bj][m][n] = __builtin_amdgcn_mfma_f32_16x16x32_bf16(Bt[n][k], At[m][k], acc[ai][bj][m][n], 0, 0, 0); __builtin_amdgcn_s_setprio(0); } while (0)
; #define PG8_WAIT_V(n) asm volatile("s_waitcnt vmcnt(" #n ")" ::: "memory")
; #define PG8_WAIT_L(n) asm volatile("s_waitcnt lgkmcnt(" #n ")" ::: "memory")
; #define PG8_BAR __builtin_amdgcn_s_barrier()
; #define PG8_SCHED __builtin_amdgcn_sched_barrier(0)
; template <class Epi, class Sched>
; __device__ __forceinline__ void gemm_phase(LAS unsigned char* lds, const int K, const Sched& S, const Epi& E) {
;     ...
;         for (int t = 0; t < nt; t += 2) {
;             const bool last = (t == nt - 2);
;             const char* a1 = cA + (size_t)(t + 1) * kstep;
;             const char* a2 = last ? nA : cA + (size_t)(t + 2) * kstep; const char* b2 = last ? nB : cB + (size_t)(t + 2) * kstep;
;             const char* a3 = a2 + kstep; const char* b3 = b2 + kstep;
;             PG8_LDB(B0, 0, 0); PG8_LDB(B1, 0, 1); PG8_SCHED; PG8_LDA(At, 0, 0); PG8_STAGE(PG8_SA(1, 1), a1 + hstep, voffA);
;             PG8_WAIT_V(8); PG8_WAIT_L(0); PG8_BAR; PG8_MMA(0, 0, At, B0); PG8_MMA(0, 1, At, B1); PG8_BAR; PG8_SCHED;
;             PG8_LDA(At, 0, 1); PG8_STAGE(PG8_SB(0, 0), b2, voffB); PG8_STAGE(PG8_SB(0, 1), b2 + hstep, voffB); PG8_STAGE(PG8_SA(0, 0), a2, voffA);
;             PG8_WAIT_V(8); PG8_WAIT_L(0); PG8_BAR; PG8_MMA(1, 0, At, B0); PG8_MMA(1, 1, At, B1); PG8_BAR; PG8_SCHED;
.LBB0_1073:
	s_add_i32 s13, s12, 2
	s_add_u32 s52, s8, 0x100
	s_addc_u32 s53, s9, 0
	s_add_i32 s14, 0, 0x10000
	s_cmp_eq_u32 s5, s12
	s_cselect_b32 s57, s0, s53
	s_cselect_b32 s56, s1, s52
	s_cselect_b32 s55, s2, s11
	s_cselect_b32 s54, s4, s10
	s_add_i32 s12, 0, 0x14000
	v_add_u32_e32 v158, s14, v164
	v_add_u32_e32 v162, s12, v164
	ds_read_b128 v[146:149], v158
	ds_read_b128 v[150:153], v158 offset:1024
	ds_read_b128 v[154:157], v158 offset:2048
	ds_read_b128 v[158:161], v158 offset:3072
	ds_read_b128 v[180:183], v162
	ds_read_b128 v[184:187], v162 offset:1024
	ds_read_b128 v[188:191], v162 offset:2048
	ds_read_b128 v[192:195], v162 offset:3072
	v_lshl_add_u64 v[162:163], s[8:9], 0, v[142:143]
	s_add_i32 m0, s61, 0xc000
	ds_read_b128 v[196:199], v166
	ds_read_b128 v[200:203], v166 offset:1024
	ds_read_b128 v[204:207], v166 offset:2048
	ds_read_b128 v[208:211], v166 offset:3072
	ds_read_b128 v[212:215], v166 offset:4096
	ds_read_b128 v[216:219], v166 offset:5120
	ds_read_b128 v[220:223], v166 offset:6144
	ds_read_b128 v[224:227], v166 offset:7168
	global_load_lds_dwordx4 v[162:163], off
	v_lshl_add_u64 v[162:163], s[8:9], 0, v[144:145]
	s_add_i32 m0, s61, 0xe000
	s_nop 0
	global_load_lds_dwordx4 v[162:163], off
	s_waitcnt vmcnt(8)
	s_waitcnt lgkmcnt(0)
	s_setprio 1
	s_barrier
	v_mfma_f32_16x16x32_bf16 v[124:127], v[146:149], v[196:199], v[124:127]
	v_mfma_f32_16x16x32_bf16 v[92:95], v[154:157], v[196:199], v[92:95]
	v_mfma_f32_16x16x32_bf16 v[120:123], v[146:149], v[204:207], v[120:123]
	v_mfma_f32_16x16x32_bf16 v[88:91], v[154:157], v[204:207], v[88:91]
	v_mfma_f32_16x16x32_bf16 v[116:119], v[146:149], v[212:215], v[116:119]
	v_mfma_f32_16x16x32_bf16 v[84:87], v[154:157], v[212:215], v[84:87]
	v_mfma_f32_16x16x32_bf16 v[112:115], v[146:149], v[220:223], v[112:115]
	v_mfma_f32_16x16x32_bf16 v[80:83], v[154:157], v[220:223], v[80:83]
	v_mfma_f32_16x16x32_bf16 v[124:127], v[150:153], v[200:203], v[124:127]
	v_mfma_f32_16x16x32_bf16 v[92:95], v[158:161], v[200:203], v[92:95]
	v_mfma_f32_16x16x32_bf16 v[120:123], v[150:153], v[208:211], v[120:123]
	v_mfma_f32_16x16x32_bf16 v[88:91], v[158:161], v[208:211], v[88:91]
	v_mfma_f32_16x16x32_bf16 v[116:119], v[150:153], v[216:219], v[116:119]
	v_mfma_f32_16x16x32_bf16 v[84:87], v[158:161], v[216:219], v[84:87]
	v_mfma_f32_16x16x32_bf16 v[112:115], v[150:153], v[224:227], v[112:115]
	v_mfma_f32_16x16x32_bf16 v[80:83], v[158:161], v[224:227], v[80:83]
	v_mfma_f32_16x16x32_bf16 v[60:63], v[180:183], v[196:199], v[60:63]
	v_mfma_f32_16x16x32_bf16 v[28:31], v[188:191], v[196:199], v[28:31]
	v_mfma_f32_16x16x32_bf16 v[56:59], v[180:183], v[204:207], v[56:59]
	v_mfma_f32_16x16x32_bf16 v[24:27], v[188:191], v[204:207], v[24:27]
	v_mfma_f32_16x16x32_bf16 v[52:55], v[180:183], v[212:215], v[52:55]
	v_mfma_f32_16x16x32_bf16 v[20:23], v[188:191], v[212:215], v[20:23]
	v_mfma_f32_16x16x32_bf16 v[48:51], v[180:183], v[220:223], v[48:51]
	v_mfma_f32_16x16x32_bf16 v[16:19], v[188:191], v[220:223], v[16:19]
	v_mfma_f32_16x16x32_bf16 v[60:63], v[184:187], v[200:203], v[60:63]
	v_mfma_f32_16x16x32_bf16 v[28:31], v[192:195], v[200:203], v[28:31]
	v_mfma_f32_16x16x32_bf16 v[56:59], v[184:187], v[208:211], v[56:59]
	v_mfma_f32_16x16x32_bf16 v[24:27], v[192:195], v[208:211], v[24:27]
	v_mfma_f32_16x16x32_bf16 v[52:55], v[184:187], v[216:219], v[52:55]
	v_mfma_f32_16x16x32_bf16 v[20:23], v[192:195], v[216:219], v[20:23]
	v_mfma_f32_16x16x32_bf16 v[48:51], v[184:187], v[224:227], v[48:51]
	v_mfma_f32_16x16x32_bf16 v[16:19], v[192:195], v[224:227], v[16:19]
	s_barrier
	s_setprio 0
	s_add_i32 s8, s14, s60
	v_lshl_add_u64 v[162:163], s[54:55], 0, v[128:129]
	s_mov_b32 m0, s8
	ds_read_b128 v[196:199], v166 offset:16384
	ds_read_b128 v[200:203], v166 offset:17408
	ds_read_b128 v[204:207], v166 offset:18432
	ds_read_b128 v[208:211], v166 offset:19456
	ds_read_b128 v[212:215], v166 offset:20480
	ds_read_b128 v[216:219], v166 offset:21504
	ds_read_b128 v[220:223], v166 offset:22528
	ds_read_b128 v[224:227], v166 offset:23552
	global_load_lds_dwordx4 v[162:163], off
	s_add_i32 m0, s8, 0x2000
	s_add_u32 s8, s54, 0xb0000
	v_lshl_add_u64 v[228:229], s[54:55], 0, v[138:139]
	s_addc_u32 s9, s55, 0
	s_add_i32 s12, s12, s60
	global_load_lds_dwordx4 v[228:229], off
	v_lshl_add_u64 v[230:231], s[8:9], 0, v[128:129]
	s_mov_b32 m0, s12
	v_lshl_add_u64 v[232:233], s[56:57], 0, v[138:139]
	global_load_lds_dwordx4 v[230:231], off
	v_lshl_add_u64 v[230:231], s[8:9], 0, v[138:139]
	s_add_i32 m0, s12, 0x2000
	s_nop 0
	global_load_lds_dwordx4 v[230:231], off
	v_lshl_add_u64 v[230:231], s[56:57], 0, v[128:129]
	s_mov_b32 m0, s61
	s_nop 0
	global_load_lds_dwordx4 v[230:231], off
	s_mov_b32 m0, s63
	s_nop 0
	global_load_lds_dwordx4 v[232:233], off
	s_waitcnt vmcnt(8)
	s_waitcnt lgkmcnt(0)
	s_setprio 1
	s_barrier
; #define PG8_STAGE(bufoff, gbase, voff) do { _Pragma("unroll") for (int _i = 0; _i < 2; ++_i) \
;         __builtin_amdgcn_global_load_lds((const unsigned*)((const char*)(gbase) + (voff)[_i]), (LAS unsigned*)(lds + (bufoff) + ldsw + _i * 8192), 16, 0, 0); } while (0)
; #define PG8_LDA(dst, b, h) do { _Pragma("unroll") for (int m = 0; m < 4; ++m) _Pragma("unroll") for (int k = 0; k < 2; ++k) dst[m][k] = *(const LAS bf16x8*)(lds + PG8_SA(b, h) + aoff + m * 2048 + k * 1024); } while (0)
; #define PG8_LDB(dst, b, h) do { _Pragma("unroll") for (int n = 0; n < 2; ++n) _Pragma("unroll") for (int k = 0; k < 2; ++k) dst[n][k] = *(const LAS bf16x8*)(lds + PG8_SB(b, h) + boff + n * 2048 + k * 1024); } while (0)
; #define PG8_MMA(ai, bj, At, Bt) do { __builtin_amdgcn_s_setprio(1); _Pragma("unroll") for (int m = 0; m < 4; ++m) _Pragma("unroll") for (int n = 0; n < 2; ++n) _Pragma("unroll") for (int k = 0; k < 2; ++k) \
;         acc[ai][bj][m][n] = __builtin_amdgcn_mfma_f32_16x16x32_bf16(Bt[n][k], At[m][k], acc[ai][bj][m][n], 0, 0, 0); __builtin_amdgcn_s_setprio(0); } while (0)
; #define PG8_WAIT_V(n) asm volatile("s_waitcnt vmcnt(" #n ")" ::: "memory")
; #define PG8_WAIT_L(n) asm volatile("s_waitcnt lgkmcnt(" #n ")" ::: "memory")
; #define PG8_BAR __builtin_amdgcn_s_barrier()
; #define PG8_SCHED __builtin_amdgcn_sched_barrier(0)
; template <class Epi, class Sched>
; __device__ __forceinline__ void gemm_phase(LAS unsigned char* lds, const int K, const Sched& S, const Epi& E) {
;     ...
;             PG8_WAIT_V(8); PG8_WAIT_L(0); PG8_BAR; PG8_MMA(1, 0, At, B0); PG8_MMA(1, 1, At, B1); PG8_BAR; PG8_SCHED;
;             PG8_LDB(B0, 1, 0); PG8_LDB(B1, 1, 1); PG8_SCHED; PG8_LDA(At, 1, 0); PG8_STAGE(PG8_SA(0, 1), a2 + hstep, voffA);
;             PG8_WAIT_V(8); PG8_WAIT_L(0); PG8_BAR; PG8_MMA(0, 0, At, B0); PG8_MMA(0, 1, At, B1); PG8_BAR; PG8_SCHED;
	v_mfma_f32_16x16x32_bf16 v[108:111], v[146:149], v[196:199], v[108:111]
	v_mfma_f32_16x16x32_bf16 v[76:79], v[154:157], v[196:199], v[76:79]
	v_mfma_f32_16x16x32_bf16 v[104:107], v[146:149], v[204:207], v[104:107]
	v_mfma_f32_16x16x32_bf16 v[72:75], v[154:157], v[204:207], v[72:75]
	v_mfma_f32_16x16x32_bf16 v[100:103], v[146:149], v[212:215], v[100:103]
	v_mfma_f32_16x16x32_bf16 v[68:71], v[154:157], v[212:215], v[68:71]
	v_mfma_f32_16x16x32_bf16 v[96:99], v[146:149], v[220:223], v[96:99]
	v_mfma_f32_16x16x32_bf16 v[64:67], v[154:157], v[220:223], v[64:67]
	v_mfma_f32_16x16x32_bf16 v[108:111], v[150:153], v[200:203], v[108:111]
	v_mfma_f32_16x16x32_bf16 v[76:79], v[158:161], v[200:203], v[76:79]
	v_mfma_f32_16x16x32_bf16 v[104:107], v[150:153], v[208:211], v[104:107]
	v_mfma_f32_16x16x32_bf16 v[72:75], v[158:161], v[208:211], v[72:75]
	v_mfma_f32_16x16x32_bf16 v[100:103], v[150:153], v[216:219], v[100:103]
	v_mfma_f32_16x16x32_bf16 v[68:71], v[158:161], v[216:219], v[68:71]
	v_mfma_f32_16x16x32_bf16 v[96:99], v[150:153], v[224:227], v[96:99]
	v_mfma_f32_16x16x32_bf16 v[64:67], v[158:161], v[224:227], v[64:67]
	v_mfma_f32_16x16x32_bf16 v[44:47], v[180:183], v[196:199], v[44:47]
	v_mfma_f32_16x16x32_bf16 v[12:15], v[188:191], v[196:199], v[12:15]
	v_mfma_f32_16x16x32_bf16 v[40:43], v[180:183], v[204:207], v[40:43]
	v_mfma_f32_16x16x32_bf16 v[8:11], v[188:191], v[204:207], v[8:11]
	v_mfma_f32_16x16x32_bf16 v[36:39], v[180:183], v[212:215], v[36:39]
	v_mfma_f32_16x16x32_bf16 v[4:7], v[188:191], v[212:215], v[4:7]
	v_mfma_f32_16x16x32_bf16 v[32:35], v[180:183], v[220:223], v[32:35]
	v_mfma_f32_16x16x32_bf16 v[0:3], v[188:191], v[220:223], v[0:3]
	v_mfma_f32_16x16x32_bf16 v[44:47], v[184:187], v[200:203], v[44:47]
	v_mfma_f32_16x16x32_bf16 v[12:15], v[192:195], v[200:203], v[12:15]
	v_mfma_f32_16x16x32_bf16 v[40:43], v[184:187], v[208:211], v[40:43]
	v_mfma_f32_16x16x32_bf16 v[8:11], v[192:195], v[208:211], v[8:11]
	v_mfma_f32_16x16x32_bf16 v[36:39], v[184:187], v[216:219], v[36:39]
	v_mfma_f32_16x16x32_bf16 v[4:7], v[192:195], v[216:219], v[4:7]
	v_mfma_f32_16x16x32_bf16 v[32:35], v[184:187], v[224:227], v[32:35]
	v_mfma_f32_16x16x32_bf16 v[0:3], v[192:195], v[224:227], v[0:3]
	s_barrier
	s_setprio 0
	s_add_i32 s12, 0, 0x18000
	s_add_i32 s14, 0, 0x1c000
	v_add_u32_e32 v158, s12, v164
	v_add_u32_e32 v167, s14, v164
	ds_read_b128 v[146:149], v158
	ds_read_b128 v[150:153], v158 offset:1024
	ds_read_b128 v[154:157], v158 offset:2048
	ds_read_b128 v[158:161], v158 offset:3072
	ds_read_b128 v[180:183], v167
	ds_read_b128 v[184:187], v167 offset:1024
	ds_read_b128 v[188:191], v167 offset:2048
	ds_read_b128 v[192:195], v167 offset:3072
	s_add_u32 s8, s56, 0xb0000
	s_addc_u32 s9, s57, 0
	s_mov_b32 m0, s64
	v_lshl_add_u64 v[234:235], s[8:9], 0, v[128:129]
	ds_read_b128 v[196:199], v166 offset:32768
	ds_read_b128 v[200:203], v166 offset:33792
	ds_read_b128 v[204:207], v166 offset:34816
	ds_read_b128 v[208:211], v166 offset:35840
	ds_read_b128 v[212:215], v166 offset:36864
	ds_read_b128 v[216:219], v166 offset:37888
	ds_read_b128 v[220:223], v166 offset:38912
	ds_read_b128 v[224:227], v166 offset:39936
	global_load_lds_dwordx4 v[234:235], off
	v_lshl_add_u64 v[234:235], s[8:9], 0, v[138:139]
	s_mov_b32 m0, s65
	s_nop 0
	global_load_lds_dwordx4 v[234:235], off
	s_waitcnt vmcnt(8)
	s_waitcnt lgkmcnt(0)
	s_setprio 1
	s_barrier
	v_mfma_f32_16x16x32_bf16 v[124:127], v[146:149], v[196:199], v[124:127]
	v_mfma_f32_16x16x32_bf16 v[92:95], v[154:157], v[196:199], v[92:95]
	v_mfma_f32_16x16x32_bf16 v[120:123], v[146:149], v[204:207], v[120:123]
	v_mfma_f32_16x16x32_bf16 v[88:91], v[154:157], v[204:207], v[88:91]
	v_mfma_f32_16x16x32_bf16 v[116:119], v[146:149], v[212:215], v[116:119]
	v_mfma_f32_16x16x32_bf16 v[84:87], v[154:157], v[212:215], v[84:87]
	v_mfma_f32_16x16x32_bf16 v[112:115], v[146:149], v[220:223], v[112:115]
	v_mfma_f32_16x16x32_bf16 v[80:83], v[154:157], v[220:223], v[80:83]
	v_mfma_f32_16x16x32_bf16 v[124:127], v[150:153], v[200:203], v[124:127]
	v_mfma_f32_16x16x32_bf16 v[92:95], v[158:161], v[200:203], v[92:95]
	v_mfma_f32_16x16x32_bf16 v[120:123], v[150:153], v[208:211], v[120:123]
	v_mfma_f32_16x16x32_bf16 v[88:91], v[158:161], v[208:211], v[88:91]
	v_mfma_f32_16x16x32_bf16 v[116:119], v[150:153], v[216:219], v[116:119]
	v_mfma_f32_16x16x32_bf16 v[84:87], v[158:161], v[216:219], v[84:87]
	v_mfma_f32_16x16x32_bf16 v[112:115], v[150:153], v[224:227], v[112:115]
	v_mfma_f32_16x16x32_bf16 v[80:83], v[158:161], v[224:227], v[80:83]
	v_mfma_f32_16x16x32_bf16 v[60:63], v[180:183], v[196:199], v[60:63]
	v_mfma_f32_16x16x32_bf16 v[28:31], v[188:191], v[196:199], v[28:31]
	v_mfma_f32_16x16x32_bf16 v[56:59], v[180:183], v[204:207], v[56:59]
	v_mfma_f32_16x16x32_bf16 v[24:27], v[188:191], v[204:207], v[24:27]
	v_mfma_f32_16x16x32_bf16 v[52:55], v[180:183], v[212:215], v[52:55]
	v_mfma_f32_16x16x32_bf16 v[20:23], v[188:191], v[212:215], v[20:23]
	v_mfma_f32_16x16x32_bf16 v[48:51], v[180:183], v[220:223], v[48:51]
	v_mfma_f32_16x16x32_bf16 v[16:19], v[188:191], v[220:223], v[16:19]
	v_mfma_f32_16x16x32_bf16 v[60:63], v[184:187], v[200:203], v[60:63]
	v_mfma_f32_16x16x32_bf16 v[28:31], v[192:195], v[200:203], v[28:31]
	v_mfma_f32_16x16x32_bf16 v[56:59], v[184:187], v[208:211], v[56:59]
	v_mfma_f32_16x16x32_bf16 v[24:27], v[192:195], v[208:211], v[24:27]
	v_mfma_f32_16x16x32_bf16 v[52:55], v[184:187], v[216:219], v[52:55]
	v_mfma_f32_16x16x32_bf16 v[20:23], v[192:195], v[216:219], v[20:23]
	v_mfma_f32_16x16x32_bf16 v[48:51], v[184:187], v[224:227], v[48:51]
	v_mfma_f32_16x16x32_bf16 v[16:19], v[192:195], v[224:227], v[16:19]
	s_barrier
; #define PG8_STAGE(bufoff, gbase, voff) do { _Pragma("unroll") for (int _i = 0; _i < 2; ++_i) \
;         __builtin_amdgcn_global_load_lds((const unsigned*)((const char*)(gbase) + (voff)[_i]), (LAS unsigned*)(lds + (bufoff) + ldsw + _i * 8192), 16, 0, 0); } while (0)
; #define PG8_LDA(dst, b, h) do { _Pragma("unroll") for (int m = 0; m < 4; ++m) _Pragma("unroll") for (int k = 0; k < 2; ++k) dst[m][k] = *(const LAS bf16x8*)(lds + PG8_SA(b, h) + aoff + m * 2048 + k * 1024); } while (0)
; #define PG8_MMA(ai, bj, At, Bt) do { __builtin_amdgcn_s_setprio(1); _Pragma("unroll") for (int m = 0; m < 4; ++m) _Pragma("unroll") for (int n = 0; n < 2; ++n) _Pragma("unroll") for (int k = 0; k < 2; ++k) \
;         acc[ai][bj][m][n] = __builtin_amdgcn_mfma_f32_16x16x32_bf16(Bt[n][k], At[m][k], acc[ai][bj][m][n], 0, 0, 0); __builtin_amdgcn_s_setprio(0); } while (0)
; #define PG8_WAIT_V(n) asm volatile("s_waitcnt vmcnt(" #n ")" ::: "memory")
; #define PG8_WAIT_L(n) asm volatile("s_waitcnt lgkmcnt(" #n ")" ::: "memory")
; #define PG8_BAR __builtin_amdgcn_s_barrier()
; #define PG8_SCHED __builtin_amdgcn_sched_barrier(0)
; template <class Epi, class Sched>
; __device__ __forceinline__ void gemm_phase(LAS unsigned char* lds, const int K, const Sched& S, const Epi& E) {
;     ...
;             PG8_LDA(At, 1, 1); PG8_STAGE(PG8_SB(1, 0), b3, voffB); PG8_STAGE(PG8_SB(1, 1), b3 + hstep, voffB); PG8_STAGE(PG8_SA(1, 0), a3, voffA);
;             PG8_WAIT_V(8); PG8_WAIT_L(0); PG8_BAR; PG8_MMA(1, 0, At, B0); PG8_MMA(1, 1, At, B1); PG8_BAR; PG8_SCHED;
;         }
;         if (wr == 0) PG8_BAR;
	s_setprio 0
	s_add_i32 s8, s12, s60
	v_lshl_add_u64 v[162:163], v[162:163], 0, s[36:37]
	s_mov_b32 m0, s8
	ds_read_b128 v[196:199], v166 offset:49152
	ds_read_b128 v[200:203], v166 offset:50176
	ds_read_b128 v[204:207], v166 offset:51200
	ds_read_b128 v[208:211], v166 offset:52224
	ds_read_b128 v[212:215], v166 offset:53248
	ds_read_b128 v[216:219], v166 offset:54272
	ds_read_b128 v[220:223], v166 offset:55296
	ds_read_b128 v[224:227], v166 offset:56320
	global_load_lds_dwordx4 v[162:163], off
	s_add_i32 m0, s8, 0x2000
	s_add_u32 s8, s54, 0xb0080
	v_lshl_add_u64 v[162:163], v[228:229], 0, s[36:37]
	s_addc_u32 s9, s55, 0
	s_add_i32 s12, s14, s60
	global_load_lds_dwordx4 v[162:163], off
	v_lshl_add_u64 v[162:163], s[8:9], 0, v[128:129]
	s_mov_b32 m0, s12
	s_nop 0
	global_load_lds_dwordx4 v[162:163], off
	v_lshl_add_u64 v[162:163], s[8:9], 0, v[138:139]
	s_add_i32 m0, s12, 0x2000
	s_nop 0
	global_load_lds_dwordx4 v[162:163], off
	v_lshl_add_u64 v[162:163], v[230:231], 0, s[36:37]
	s_mov_b32 m0, s68
	s_nop 0
	global_load_lds_dwordx4 v[162:163], off
	v_lshl_add_u64 v[162:163], v[232:233], 0, s[36:37]
	s_mov_b32 m0, s69
	s_nop 0
	global_load_lds_dwordx4 v[162:163], off
	s_waitcnt vmcnt(8)
	s_waitcnt lgkmcnt(0)
	s_setprio 1
	s_barrier
	v_mfma_f32_16x16x32_bf16 v[108:111], v[146:149], v[196:199], v[108:111]
	v_mfma_f32_16x16x32_bf16 v[76:79], v[154:157], v[196:199], v[76:79]
	v_mfma_f32_16x16x32_bf16 v[104:107], v[146:149], v[204:207], v[104:107]
	v_mfma_f32_16x16x32_bf16 v[72:75], v[154:157], v[204:207], v[72:75]
	v_mfma_f32_16x16x32_bf16 v[100:103], v[146:149], v[212:215], v[100:103]
	v_mfma_f32_16x16x32_bf16 v[68:71], v[154:157], v[212:215], v[68:71]
	v_mfma_f32_16x16x32_bf16 v[96:99], v[146:149], v[220:223], v[96:99]
	v_mfma_f32_16x16x32_bf16 v[64:67], v[154:157], v[220:223], v[64:67]
	v_mfma_f32_16x16x32_bf16 v[108:111], v[150:153], v[200:203], v[108:111]
	v_mfma_f32_16x16x32_bf16 v[76:79], v[158:161], v[200:203], v[76:79]
	v_mfma_f32_16x16x32_bf16 v[104:107], v[150:153], v[208:211], v[104:107]
	v_mfma_f32_16x16x32_bf16 v[72:75], v[158:161], v[208:211], v[72:75]
	v_mfma_f32_16x16x32_bf16 v[100:103], v[150:153], v[216:219], v[100:103]
	v_mfma_f32_16x16x32_bf16 v[68:71], v[158:161], v[216:219], v[68:71]
	v_mfma_f32_16x16x32_bf16 v[96:99], v[150:153], v[224:227], v[96:99]
	v_mfma_f32_16x16x32_bf16 v[64:67], v[158:161], v[224:227], v[64:67]
	v_mfma_f32_16x16x32_bf16 v[44:47], v[180:183], v[196:199], v[44:47]
	v_mfma_f32_16x16x32_bf16 v[12:15], v[188:191], v[196:199], v[12:15]
	v_mfma_f32_16x16x32_bf16 v[40:43], v[180:183], v[204:207], v[40:43]
	v_mfma_f32_16x16x32_bf16 v[8:11], v[188:191], v[204:207], v[8:11]
	v_mfma_f32_16x16x32_bf16 v[36:39], v[180:183], v[212:215], v[36:39]
	v_mfma_f32_16x16x32_bf16 v[4:7], v[188:191], v[212:215], v[4:7]
	v_mfma_f32_16x16x32_bf16 v[32:35], v[180:183], v[220:223], v[32:35]
	v_mfma_f32_16x16x32_bf16 v[0:3], v[188:191], v[220:223], v[0:3]
	v_mfma_f32_16x16x32_bf16 v[44:47], v[184:187], v[200:203], v[44:47]
	v_mfma_f32_16x16x32_bf16 v[12:15], v[192:195], v[200:203], v[12:15]
	v_mfma_f32_16x16x32_bf16 v[40:43], v[184:187], v[208:211], v[40:43]
	v_mfma_f32_16x16x32_bf16 v[8:11], v[192:195], v[208:211], v[8:11]
	v_mfma_f32_16x16x32_bf16 v[36:39], v[184:187], v[216:219], v[36:39]
	v_mfma_f32_16x16x32_bf16 v[4:7], v[192:195], v[216:219], v[4:7]
	v_mfma_f32_16x16x32_bf16 v[32:35], v[184:187], v[224:227], v[32:35]
	v_mfma_f32_16x16x32_bf16 v[0:3], v[192:195], v[224:227], v[0:3]
	s_barrier
	s_setprio 0
	s_add_u32 s10, s10, 0x100
	s_addc_u32 s11, s11, 0
	s_cmp_ge_i32 s13, s51
	s_mov_b64 s[8:9], s[52:53]
	s_mov_b32 s12, s13
	s_cbranch_scc0 .LBB0_1073
	s_and_b64 vcc, exec, s[40:41]
	s_cbranch_vccz .LBB0_1076
